# up-proj units: the epilogue's 8 per-row sum loads (sc1) issued at the unit header, before the K-loop, into spare registers; epilogue copies them (on v81)
# speedup vs baseline: 1.0043x; 1.0043x over previous
;     __host__ __device__ bool next(int i, Unit& u) const { if (!StaticOrder::next(i >> 1, u)) return false; u.kh = i & 1; u.slot = i >> 1; return true; }
;     __host__ __device__ bool next(int i, Unit& u) const {
;         const long L = (long)i * G + c; if (L >= nwg) return false;
;         int wgid = (int)L; { const int q = nwg / NXCD, r = nwg % NXCD, xcd = wgid % NXCD, off = wgid / NXCD; wgid = (xcd < r ? xcd * (q + 1) : r * (q + 1) + (xcd - r) * q) + off; }
;         const int nig = wgm * nN, gid = wgid / nig, fm = gid * wgm, gsz = (nM - fm) < wgm ? (nM - fm) : wgm;
;     __device__ __forceinline__ void operator()(const f32x4 (&acc)[2][2][4][2], const Unit& u, int wr, int wc, int fr, int fq) const {
;     ...
;                 const int row = row0 + ai * HALF + m * 16; const float rs = 1.0f / sqrtf(__hip_atomic_load(ss2 + row, __ATOMIC_RELAXED, __HIP_MEMORY_SCOPE_AGENT) * (1.0f / 2048.0f) + EPSN);
.LBB0_854:
	v_lshl_add_u32 v236, s4, 8, v152
	v_ashrrev_i32_e32 v237, 31, v236
	v_lshl_add_u64 v[236:237], v[236:237], 2, s[38:39]
	global_load_dword v238, v[236:237], off sc1
	global_load_dword v239, v[236:237], off offset:64 sc1
	global_load_dword v240, v[236:237], off offset:128 sc1
	global_load_dword v241, v[236:237], off offset:192 sc1
	global_load_dword v242, v[236:237], off offset:512 sc1
	global_load_dword v243, v[236:237], off offset:576 sc1
	global_load_dword v244, v[236:237], off offset:640 sc1
	global_load_dword v245, v[236:237], off offset:704 sc1
	s_nop 0
	s_add_i32 s67, s67, 1
	s_mul_i32 s1, s67, s70
	s_mul_hi_u32 s2, s67, s71
	s_add_i32 s2, s2, s1
	s_mul_i32 s1, s67, s71
	s_add_u32 s52, s1, s12
	s_addc_u32 s53, s2, s13
	v_cmp_gt_i64_e32 vcc, s[52:53], v[142:143]
	v_cmp_lt_i64_e64 s[2:3], s[52:53], v[140:141]
	s_cbranch_vccnz .LBB0_860
	s_ashr_i32 s1, s52, 31
	s_lshr_b32 s1, s1, 29
	s_add_i32 s1, s52, s1
	s_and_b32 s5, s1, -8
	s_sub_i32 s5, s52, s5
	s_cmp_gt_i32 s5, -1
	s_mov_b64 s[48:49], -1
	s_cbranch_scc0 .LBB0_857
	s_lshl_b32 s50, s5, 7
	s_mov_b64 s[48:49], 0

;     __host__ __device__ bool next(int i, Unit& u) const { if (!StaticOrder::next(i >> 1, u)) return false; u.kh = i & 1; u.slot = i >> 1; return true; }
; template <class Epi, class Sched, bool ALIGN_EPI = false, bool SP2 = false>
; __device__ __forceinline__ void gemm_phase(PG8_LAS unsigned char* lds, const Gemm g, const Sched& S, const Epi& E) {
;     ...
;         const bool has_next = S.next(ui + 1, nxt);
;         const char* nA = has_next ? (const char*)g.A + (size_t)nxt.pm * tstep + nxt.kh * khstep : cA; const char* nB = has_next ? (const char*)g.Bt + (size_t)nxt.pn * tstep + nxt.kh * khstep : cB;
;         for (int t = 0; t < nt; t += 2) {
;             const bool last = (t == nt - 2);
;             const char* a1 = cA + (size_t)(t + 1) * kstep;
;             const char* a2 = last ? nA : cA + (size_t)(t + 2) * kstep; const char* b2 = last ? nB : cB + (size_t)(t + 2) * kstep;
;     ...
; #pragma unroll
;         for (int a = 0; a < 2; ++a)
; #pragma unroll
;             for (int b = 0; b < 2; ++b)
; #pragma unroll
;                 for (int m = 0; m < 4; ++m)
; #pragma unroll
;                     for (int n = 0; n < 2; ++n) acc[a][b][m][n] = (f32x4){0.f, 0.f, 0.f, 0.f};
;         }
;         cur = nxt; cA = nA; cB = nB; ++ui;
.LBB0_860:
	s_ashr_i32 s51, s50, 31
	s_lshl_b64 s[52:53], s[50:51], 20
	s_add_u32 s52, s36, s52
	s_addc_u32 s53, s37, s53
	s_and_b64 s[54:55], s[2:3], exec
	s_cselect_b32 s1, s53, s57
	s_cselect_b32 s5, s52, s56
	s_ashr_i32 s49, s48, 31
	s_lshl_b64 s[54:55], s[48:49], 20
	s_add_u32 s54, s8, s54
	s_addc_u32 s55, s9, s55
	s_and_b64 s[60:61], s[2:3], exec
	s_cselect_b32 s49, s55, s59
	s_cselect_b32 s51, s54, s58
	s_add_u32 s56, s56, 0x80080
	s_addc_u32 s57, s57, 0
	s_add_u32 s80, s58, 0x100
	v_mov_b32_e32 v0, 0
	s_addc_u32 s81, s59, 0
	s_mov_b32 s82, -2
	v_mov_b32_e32 v1, v0
	v_mov_b32_e32 v2, v0
	v_mov_b32_e32 v3, v0
	v_mov_b32_e32 v4, v0
	v_mov_b32_e32 v5, v0
	v_mov_b32_e32 v6, v0
	v_mov_b32_e32 v7, v0
	v_mov_b32_e32 v16, v0
	v_mov_b32_e32 v17, v0
	v_mov_b32_e32 v18, v0
	v_mov_b32_e32 v19, v0
	v_mov_b32_e32 v20, v0
	v_mov_b32_e32 v21, v0
	v_mov_b32_e32 v22, v0
	v_mov_b32_e32 v23, v0
	v_mov_b32_e32 v32, v0
	v_mov_b32_e32 v33, v0
	v_mov_b32_e32 v34, v0
	v_mov_b32_e32 v35, v0
	v_mov_b32_e32 v36, v0
	v_mov_b32_e32 v37, v0
	v_mov_b32_e32 v38, v0
	v_mov_b32_e32 v39, v0
	v_mov_b32_e32 v48, v0
	v_mov_b32_e32 v49, v0
	v_mov_b32_e32 v50, v0
	v_mov_b32_e32 v51, v0
	v_mov_b32_e32 v52, v0
	v_mov_b32_e32 v53, v0
	v_mov_b32_e32 v54, v0
	v_mov_b32_e32 v55, v0
	v_mov_b32_e32 v8, v0
	v_mov_b32_e32 v9, v0
	v_mov_b32_e32 v10, v0
	v_mov_b32_e32 v11, v0
	v_mov_b32_e32 v12, v0
	v_mov_b32_e32 v13, v0
	v_mov_b32_e32 v14, v0
	v_mov_b32_e32 v15, v0
	s_waitcnt vmcnt(24)
	v_mov_b32_e32 v24, v0
	v_mov_b32_e32 v25, v0
	v_mov_b32_e32 v26, v0
	v_mov_b32_e32 v27, v0
	v_mov_b32_e32 v28, v0
	v_mov_b32_e32 v29, v0
	v_mov_b32_e32 v30, v0
	v_mov_b32_e32 v31, v0
	v_mov_b32_e32 v40, v0
	v_mov_b32_e32 v41, v0
	v_mov_b32_e32 v42, v0
	v_mov_b32_e32 v43, v0
	v_mov_b32_e32 v44, v0
	v_mov_b32_e32 v45, v0
	v_mov_b32_e32 v46, v0
	v_mov_b32_e32 v47, v0
	v_mov_b32_e32 v56, v0
	v_mov_b32_e32 v57, v0
	v_mov_b32_e32 v58, v0
	v_mov_b32_e32 v59, v0
	v_mov_b32_e32 v60, v0
	v_mov_b32_e32 v61, v0
	v_mov_b32_e32 v62, v0
	v_mov_b32_e32 v63, v0
	v_mov_b32_e32 v64, v0
	v_mov_b32_e32 v65, v0
	v_mov_b32_e32 v66, v0
	v_mov_b32_e32 v67, v0
	v_mov_b32_e32 v68, v0
	v_mov_b32_e32 v69, v0
	v_mov_b32_e32 v70, v0
	v_mov_b32_e32 v71, v0
	v_mov_b32_e32 v80, v0
	v_mov_b32_e32 v81, v0
	v_mov_b32_e32 v82, v0
	v_mov_b32_e32 v83, v0
	v_mov_b32_e32 v84, v0
	v_mov_b32_e32 v85, v0
	v_mov_b32_e32 v86, v0
	v_mov_b32_e32 v87, v0
	v_mov_b32_e32 v96, v0
	v_mov_b32_e32 v97, v0
	v_mov_b32_e32 v98, v0
	v_mov_b32_e32 v99, v0
	v_mov_b32_e32 v100, v0
	v_mov_b32_e32 v101, v0
	v_mov_b32_e32 v102, v0
	v_mov_b32_e32 v103, v0
	v_mov_b32_e32 v112, v0
	v_mov_b32_e32 v113, v0
	v_mov_b32_e32 v114, v0
	v_mov_b32_e32 v115, v0
	v_mov_b32_e32 v116, v0
	v_mov_b32_e32 v117, v0
	v_mov_b32_e32 v118, v0
	v_mov_b32_e32 v119, v0
	v_mov_b32_e32 v72, v0
	v_mov_b32_e32 v73, v0
	v_mov_b32_e32 v74, v0
	v_mov_b32_e32 v75, v0
	v_mov_b32_e32 v76, v0
	v_mov_b32_e32 v77, v0
	v_mov_b32_e32 v78, v0
	v_mov_b32_e32 v79, v0
	v_mov_b32_e32 v88, v0
	v_mov_b32_e32 v89, v0
	v_mov_b32_e32 v90, v0
	v_mov_b32_e32 v91, v0
	v_mov_b32_e32 v92, v0
	v_mov_b32_e32 v93, v0
	v_mov_b32_e32 v94, v0
	v_mov_b32_e32 v95, v0
	v_mov_b32_e32 v104, v0
	v_mov_b32_e32 v105, v0
	v_mov_b32_e32 v106, v0
	v_mov_b32_e32 v107, v0
	v_mov_b32_e32 v108, v0
	v_mov_b32_e32 v109, v0
	v_mov_b32_e32 v110, v0
	v_mov_b32_e32 v111, v0
	v_mov_b32_e32 v120, v0
	v_mov_b32_e32 v121, v0
	v_mov_b32_e32 v122, v0
	v_mov_b32_e32 v123, v0
	v_mov_b32_e32 v124, v0
	v_mov_b32_e32 v125, v0
	v_mov_b32_e32 v126, v0
	v_mov_b32_e32 v127, v0

; __device__ __forceinline__ unsigned cvt_pk_bf16(float lo, float hi) { unsigned r; asm volatile("v_cvt_pk_bf16_f32 %0, %1, %2" : "=v"(r) : "v"(lo), "v"(hi)); return r; }
;     __device__ __forceinline__ void operator()(const f32x4 (&acc)[2][2][4][2], const Unit& u, int wr, int wc, int fr, int fq) const {
;         const int row0 = u.pm * BM + wr * 64 + fr, col0 = u.pn * BM + wc * 32 + 8 * fq;
; #pragma unroll
;         for (int ai = 0; ai < 2; ++ai)
; #pragma unroll
;             for (int m = 0; m < 4; ++m) {
;                 const int row = row0 + ai * HALF + m * 16; const float rs = 1.0f / sqrtf(__hip_atomic_load(ss2 + row, __ATOMIC_RELAXED, __HIP_MEMORY_SCOPE_AGENT) * (1.0f / 2048.0f) + EPSN);
;                 bf16_t* rowp = H + (size_t)row * DFF + col0;
; #pragma unroll
;                 for (int bj = 0; bj < 2; ++bj) {
;                     f32x4 v0 = acc[ai][bj][m][0] * rs, v1 = acc[ai][bj][m][1] * rs;
; #pragma unroll
;                     for (int j = 0; j < 4; ++j) { v0[j] = fmaxf(v0[j], 0.f); v0[j] *= v0[j]; v1[j] = fmaxf(v1[j], 0.f); v1[j] *= v1[j]; }
;                     u32x4 w; w.x = cvt_pk_bf16(v0[0], v0[1]); w.y = cvt_pk_bf16(v0[2], v0[3]); w.z = cvt_pk_bf16(v1[0], v1[1]); w.w = cvt_pk_bf16(v1[2], v1[3]);
;                     *(u32x4*)(rowp + bj * HALF) = w;
.LBB0_864:
	v_lshl_add_u32 v150, s4, 8, v152
	v_ashrrev_i32_e32 v151, 31, v150
	v_lshl_add_u64 v[144:145], v[150:151], 2, s[38:39]
	v_mov_b32_e32 v161, v238
	v_mov_b32_e32 v228, v239
	v_mov_b32_e32 v229, v240
	v_mov_b32_e32 v230, v241
	v_mov_b32_e32 v231, v242
	v_mov_b32_e32 v232, v243
	v_mov_b32_e32 v233, v244
	v_mov_b32_e32 v234, v245
	v_lshl_or_b32 v146, s0, 8, v154
	v_ashrrev_i32_e32 v147, 31, v146
	v_lshlrev_b64 v[148:149], 1, v[146:147]
	v_lshlrev_b64 v[164:165], 14, v[150:151]
	v_or_b32_e32 v162, 16, v150
	v_ashrrev_i32_e32 v163, 31, v162
	s_nop 0
	v_fmamk_f32 v146, v161, 0x3a000000, v158
	v_mul_f32_e32 v147, 0x4f800000, v146
	v_cmp_gt_f32_e32 vcc, s75, v146
	s_nop 1
	v_cndmask_b32_e32 v151, v146, v147, vcc
	v_sqrt_f32_e32 v161, v151
	v_lshl_add_u64 v[146:147], s[10:11], 0, v[164:165]
	v_lshl_add_u64 v[146:147], v[146:147], 0, v[148:149]
	v_lshl_add_u64 v[164:165], v[162:163], 2, s[38:39]
	v_add_u32_e32 v166, -1, v161
	v_add_u32_e32 v167, 1, v161
	v_fma_f32 v168, -v166, v161, v151
	v_fma_f32 v169, -v167, v161, v151
	v_cmp_ge_f32_e64 s[4:5], 0, v168
	s_nop 1
	v_cndmask_b32_e64 v161, v161, v166, s[4:5]
	v_cmp_lt_f32_e64 s[4:5], 0, v169
	s_nop 1
	v_cndmask_b32_e64 v161, v161, v167, s[4:5]
	v_mul_f32_e32 v166, 0x37800000, v161
	v_cndmask_b32_e32 v161, v161, v166, vcc
	v_cmp_class_f32_e32 vcc, v151, v159
	s_nop 1
	v_cndmask_b32_e32 v151, v161, v151, vcc
	v_div_scale_f32 v161, s[0:1], v151, v151, 1.0
	v_rcp_f32_e32 v166, v161
	v_div_scale_f32 v167, vcc, 1.0, v151, 1.0
	v_fma_f32 v168, -v161, v166, 1.0
	v_fmac_f32_e32 v166, v168, v166
	v_mul_f32_e32 v168, v167, v166
	v_fma_f32 v169, -v161, v168, v167
	v_fmac_f32_e32 v168, v169, v166
	v_fma_f32 v161, -v161, v168, v167
	v_div_fmas_f32 v161, v161, v166, v168
	v_div_fixup_f32 v166, v161, v151, 1.0
	v_pk_mul_f32 v[126:127], v[126:127], v[166:167] op_sel_hi:[1,0]
	v_pk_mul_f32 v[124:125], v[124:125], v[166:167] op_sel_hi:[1,0]
	v_pk_mul_f32 v[122:123], v[122:123], v[166:167] op_sel_hi:[1,0]
	v_pk_mul_f32 v[120:121], v[120:121], v[166:167] op_sel_hi:[1,0]
	v_pk_mul_f32 v[114:115], v[114:115], v[166:167] op_sel_hi:[1,0]
	v_pk_mul_f32 v[112:113], v[112:113], v[166:167] op_sel_hi:[1,0]
	v_pk_mul_f32 v[118:119], v[118:119], v[166:167] op_sel_hi:[1,0]
	v_pk_mul_f32 v[116:117], v[116:117], v[166:167] op_sel_hi:[1,0]
	v_max_f32_e32 v124, 0, v124
	v_max_f32_e32 v120, 0, v120
	v_max_f32_e32 v125, 0, v125
	v_max_f32_e32 v121, 0, v121
	v_max_f32_e32 v126, 0, v126
	v_max_f32_e32 v122, 0, v122
	v_max_f32_e32 v127, 0, v127
	v_max_f32_e32 v123, 0, v123
	v_max_f32_e32 v112, 0, v112
	v_max_f32_e32 v113, 0, v113
	v_max_f32_e32 v114, 0, v114
	v_max_f32_e32 v115, 0, v115
	v_max_f32_e32 v116, 0, v116
	v_max_f32_e32 v117, 0, v117
	v_max_f32_e32 v118, 0, v118
	v_max_f32_e32 v119, 0, v119
	v_mul_f32_e32 v124, v124, v124
	v_mul_f32_e32 v120, v120, v120
	v_mul_f32_e32 v125, v125, v125
	v_mul_f32_e32 v121, v121, v121
	v_mul_f32_e32 v126, v126, v126
	v_mul_f32_e32 v122, v122, v122
	v_mul_f32_e32 v127, v127, v127
	v_mul_f32_e32 v123, v123, v123
	v_mul_f32_e32 v151, v112, v112
	v_mul_f32_e32 v161, v113, v113
	v_mul_f32_e32 v166, v114, v114
	v_mul_f32_e32 v167, v115, v115
	v_cvt_pk_bf16_f32 v112, v124, v125
	v_cvt_pk_bf16_f32 v113, v126, v127
	v_cvt_pk_bf16_f32 v114, v120, v121
	v_cvt_pk_bf16_f32 v115, v122, v123
	v_mul_f32_e32 v116, v116, v116
	v_mul_f32_e32 v117, v117, v117
	v_mul_f32_e32 v118, v118, v118
	v_mul_f32_e32 v119, v119, v119
	global_store_dwordx4 v[146:147], v[112:115], off
	s_nop 1
	v_cvt_pk_bf16_f32 v112, v116, v117
	v_cvt_pk_bf16_f32 v113, v118, v119
	v_cvt_pk_bf16_f32 v114, v151, v161
	v_cvt_pk_bf16_f32 v115, v166, v167
	global_store_dwordx4 v[146:147], v[112:115], off offset:256
	s_nop 0
	s_nop 0
	v_or_b32_e32 v112, 32, v150
	v_ashrrev_i32_e32 v113, 31, v112
	v_lshl_add_u64 v[116:117], v[112:113], 2, s[38:39]
	s_nop 0
	v_fmamk_f32 v114, v228, 0x3a000000, v158
	v_mul_f32_e32 v115, 0x4f800000, v114
	v_cmp_gt_f32_e32 vcc, s75, v114
	s_nop 1
	v_cndmask_b32_e32 v118, v114, v115, vcc
	v_sqrt_f32_e32 v119, v118
	v_lshlrev_b64 v[114:115], 14, v[162:163]
	v_lshl_add_u64 v[114:115], s[10:11], 0, v[114:115]
	v_lshl_add_u64 v[114:115], v[114:115], 0, v[148:149]
	v_add_u32_e32 v120, -1, v119
	v_add_u32_e32 v121, 1, v119
	v_fma_f32 v122, -v120, v119, v118
	v_fma_f32 v123, -v121, v119, v118
	v_cmp_ge_f32_e64 s[4:5], 0, v122
	s_nop 1
	v_cndmask_b32_e64 v119, v119, v120, s[4:5]
	v_cmp_lt_f32_e64 s[4:5], 0, v123
	s_nop 1
	v_cndmask_b32_e64 v119, v119, v121, s[4:5]
	v_mul_f32_e32 v120, 0x37800000, v119
	v_cndmask_b32_e32 v119, v119, v120, vcc
	v_cmp_class_f32_e32 vcc, v118, v159
	s_nop 1
	v_cndmask_b32_e32 v118, v119, v118, vcc
	v_div_scale_f32 v119, s[0:1], v118, v118, 1.0
	v_rcp_f32_e32 v120, v119
	v_div_scale_f32 v121, vcc, 1.0, v118, 1.0
	v_fma_f32 v122, -v119, v120, 1.0
	v_fmac_f32_e32 v120, v122, v120
	v_mul_f32_e32 v122, v121, v120
	v_fma_f32 v123, -v119, v122, v121
	v_fmac_f32_e32 v122, v123, v120
	v_fma_f32 v119, -v119, v122, v121
	v_div_fmas_f32 v119, v119, v120, v122
	v_div_fixup_f32 v118, v119, v118, 1.0
	v_pk_mul_f32 v[110:111], v[110:111], v[118:119] op_sel_hi:[1,0]
	v_pk_mul_f32 v[108:109], v[108:109], v[118:119] op_sel_hi:[1,0]
	v_pk_mul_f32 v[106:107], v[106:107], v[118:119] op_sel_hi:[1,0]
	v_pk_mul_f32 v[104:105], v[104:105], v[118:119] op_sel_hi:[1,0]
	v_pk_mul_f32 v[98:99], v[98:99], v[118:119] op_sel_hi:[1,0]
	v_pk_mul_f32 v[96:97], v[96:97], v[118:119] op_sel_hi:[1,0]
	v_pk_mul_f32 v[102:103], v[102:103], v[118:119] op_sel_hi:[1,0]
	v_pk_mul_f32 v[100:101], v[100:101], v[118:119] op_sel_hi:[1,0]
	v_max_f32_e32 v108, 0, v108
	v_max_f32_e32 v104, 0, v104
	v_max_f32_e32 v109, 0, v109
	v_max_f32_e32 v105, 0, v105
; __device__ __forceinline__ unsigned cvt_pk_bf16(float lo, float hi) { unsigned r; asm volatile("v_cvt_pk_bf16_f32 %0, %1, %2" : "=v"(r) : "v"(lo), "v"(hi)); return r; }
;     __device__ __forceinline__ void operator()(const f32x4 (&acc)[2][2][4][2], const Unit& u, int wr, int wc, int fr, int fq) const {
;         const int row0 = u.pm * BM + wr * 64 + fr, col0 = u.pn * BM + wc * 32 + 8 * fq;
; #pragma unroll
;         for (int ai = 0; ai < 2; ++ai)
; #pragma unroll
;             for (int m = 0; m < 4; ++m) {
;                 const int row = row0 + ai * HALF + m * 16; const float rs = 1.0f / sqrtf(__hip_atomic_load(ss2 + row, __ATOMIC_RELAXED, __HIP_MEMORY_SCOPE_AGENT) * (1.0f / 2048.0f) + EPSN);
;                 bf16_t* rowp = H + (size_t)row * DFF + col0;
; #pragma unroll
;                 for (int bj = 0; bj < 2; ++bj) {
;                     f32x4 v0 = acc[ai][bj][m][0] * rs, v1 = acc[ai][bj][m][1] * rs;
; #pragma unroll
;                     for (int j = 0; j < 4; ++j) { v0[j] = fmaxf(v0[j], 0.f); v0[j] *= v0[j]; v1[j] = fmaxf(v1[j], 0.f); v1[j] *= v1[j]; }
;                     u32x4 w; w.x = cvt_pk_bf16(v0[0], v0[1]); w.y = cvt_pk_bf16(v0[2], v0[3]); w.z = cvt_pk_bf16(v1[0], v1[1]); w.w = cvt_pk_bf16(v1[2], v1[3]);
;                     *(u32x4*)(rowp + bj * HALF) = w;
	v_max_f32_e32 v110, 0, v110
	v_max_f32_e32 v106, 0, v106
	v_max_f32_e32 v111, 0, v111
	v_max_f32_e32 v107, 0, v107
	v_max_f32_e32 v96, 0, v96
	v_max_f32_e32 v97, 0, v97
	v_max_f32_e32 v98, 0, v98
	v_max_f32_e32 v99, 0, v99
	v_max_f32_e32 v100, 0, v100
	v_max_f32_e32 v101, 0, v101
	v_max_f32_e32 v102, 0, v102
	v_max_f32_e32 v103, 0, v103
	v_mul_f32_e32 v108, v108, v108
	v_mul_f32_e32 v104, v104, v104
	v_mul_f32_e32 v109, v109, v109
	v_mul_f32_e32 v105, v105, v105
	v_mul_f32_e32 v110, v110, v110
	v_mul_f32_e32 v106, v106, v106
	v_mul_f32_e32 v111, v111, v111
	v_mul_f32_e32 v107, v107, v107
	v_mul_f32_e32 v118, v96, v96
	v_mul_f32_e32 v119, v97, v97
	v_mul_f32_e32 v120, v98, v98
	v_mul_f32_e32 v121, v99, v99
	v_cvt_pk_bf16_f32 v96, v108, v109
	v_cvt_pk_bf16_f32 v97, v110, v111
	v_cvt_pk_bf16_f32 v98, v104, v105
	v_cvt_pk_bf16_f32 v99, v106, v107
	v_mul_f32_e32 v100, v100, v100
	v_mul_f32_e32 v101, v101, v101
	v_mul_f32_e32 v102, v102, v102
	v_mul_f32_e32 v103, v103, v103
	global_store_dwordx4 v[114:115], v[96:99], off
	s_nop 1
	v_cvt_pk_bf16_f32 v96, v100, v101
	v_cvt_pk_bf16_f32 v97, v102, v103
	v_cvt_pk_bf16_f32 v98, v118, v119
	v_cvt_pk_bf16_f32 v99, v120, v121
	global_store_dwordx4 v[114:115], v[96:99], off offset:256
	s_nop 0
	s_nop 0
	v_or_b32_e32 v96, 48, v150
	v_ashrrev_i32_e32 v97, 31, v96
	v_lshl_add_u64 v[100:101], v[96:97], 2, s[38:39]
	s_nop 0
	v_fmamk_f32 v98, v229, 0x3a000000, v158
	v_mul_f32_e32 v99, 0x4f800000, v98
	v_cmp_gt_f32_e32 vcc, s75, v98
	s_nop 1
	v_cndmask_b32_e32 v102, v98, v99, vcc
	v_sqrt_f32_e32 v103, v102
	v_lshlrev_b64 v[98:99], 14, v[112:113]
	v_lshl_add_u64 v[98:99], s[10:11], 0, v[98:99]
	v_lshl_add_u64 v[98:99], v[98:99], 0, v[148:149]
	v_add_u32_e32 v104, -1, v103
	v_add_u32_e32 v105, 1, v103
	v_fma_f32 v106, -v104, v103, v102
	v_fma_f32 v107, -v105, v103, v102
	v_cmp_ge_f32_e64 s[4:5], 0, v106
	s_nop 1
	v_cndmask_b32_e64 v103, v103, v104, s[4:5]
	v_cmp_lt_f32_e64 s[4:5], 0, v107
	s_nop 1
	v_cndmask_b32_e64 v103, v103, v105, s[4:5]
	v_mul_f32_e32 v104, 0x37800000, v103
	v_cndmask_b32_e32 v103, v103, v104, vcc
	v_cmp_class_f32_e32 vcc, v102, v159
	s_nop 1
	v_cndmask_b32_e32 v102, v103, v102, vcc
	v_div_scale_f32 v103, s[0:1], v102, v102, 1.0
	v_rcp_f32_e32 v104, v103
	v_div_scale_f32 v105, vcc, 1.0, v102, 1.0
	v_fma_f32 v106, -v103, v104, 1.0
	v_fmac_f32_e32 v104, v106, v104
	v_mul_f32_e32 v106, v105, v104
	v_fma_f32 v107, -v103, v106, v105
	v_fmac_f32_e32 v106, v107, v104
	v_fma_f32 v103, -v103, v106, v105
	v_div_fmas_f32 v103, v103, v104, v106
	v_div_fixup_f32 v102, v103, v102, 1.0
	v_pk_mul_f32 v[94:95], v[94:95], v[102:103] op_sel_hi:[1,0]
	v_pk_mul_f32 v[92:93], v[92:93], v[102:103] op_sel_hi:[1,0]
	v_pk_mul_f32 v[90:91], v[90:91], v[102:103] op_sel_hi:[1,0]
	v_pk_mul_f32 v[88:89], v[88:89], v[102:103] op_sel_hi:[1,0]
	v_pk_mul_f32 v[82:83], v[82:83], v[102:103] op_sel_hi:[1,0]
	v_pk_mul_f32 v[80:81], v[80:81], v[102:103] op_sel_hi:[1,0]
	v_pk_mul_f32 v[86:87], v[86:87], v[102:103] op_sel_hi:[1,0]
	v_pk_mul_f32 v[84:85], v[84:85], v[102:103] op_sel_hi:[1,0]
	v_max_f32_e32 v92, 0, v92
	v_max_f32_e32 v88, 0, v88
	v_max_f32_e32 v93, 0, v93
	v_max_f32_e32 v89, 0, v89
	v_max_f32_e32 v94, 0, v94
	v_max_f32_e32 v90, 0, v90
	v_max_f32_e32 v95, 0, v95
	v_max_f32_e32 v91, 0, v91
	v_max_f32_e32 v80, 0, v80
	v_max_f32_e32 v81, 0, v81
	v_max_f32_e32 v82, 0, v82
	v_max_f32_e32 v83, 0, v83
	v_max_f32_e32 v84, 0, v84
	v_max_f32_e32 v85, 0, v85
	v_max_f32_e32 v86, 0, v86
	v_max_f32_e32 v87, 0, v87
	v_mul_f32_e32 v92, v92, v92
	v_mul_f32_e32 v88, v88, v88
	v_mul_f32_e32 v93, v93, v93
	v_mul_f32_e32 v89, v89, v89
	v_mul_f32_e32 v94, v94, v94
	v_mul_f32_e32 v90, v90, v90
	v_mul_f32_e32 v95, v95, v95
	v_mul_f32_e32 v91, v91, v91
	v_mul_f32_e32 v102, v80, v80
	v_mul_f32_e32 v103, v81, v81
	v_mul_f32_e32 v104, v82, v82
	v_mul_f32_e32 v105, v83, v83
	v_cvt_pk_bf16_f32 v80, v92, v93
	v_cvt_pk_bf16_f32 v81, v94, v95
	v_cvt_pk_bf16_f32 v82, v88, v89
	v_cvt_pk_bf16_f32 v83, v90, v91
	v_mul_f32_e32 v84, v84, v84
	v_mul_f32_e32 v85, v85, v85
	v_mul_f32_e32 v86, v86, v86
	v_mul_f32_e32 v87, v87, v87
	global_store_dwordx4 v[98:99], v[80:83], off
	s_nop 1
	v_cvt_pk_bf16_f32 v80, v84, v85
	v_cvt_pk_bf16_f32 v81, v86, v87
	v_cvt_pk_bf16_f32 v82, v102, v103
	v_cvt_pk_bf16_f32 v83, v104, v105
	global_store_dwordx4 v[98:99], v[80:83], off offset:256
	s_nop 0
	s_nop 0
	v_fmamk_f32 v80, v230, 0x3a000000, v158
	v_mul_f32_e32 v81, 0x4f800000, v80
	v_cmp_gt_f32_e32 vcc, s75, v80
	s_nop 1
	v_cndmask_b32_e32 v82, v80, v81, vcc
	v_sqrt_f32_e32 v83, v82
	v_lshlrev_b64 v[80:81], 14, v[96:97]
	v_lshl_add_u64 v[80:81], s[10:11], 0, v[80:81]
	v_lshl_add_u64 v[80:81], v[80:81], 0, v[148:149]
	v_add_u32_e32 v84, -1, v83
	v_add_u32_e32 v85, 1, v83
	v_fma_f32 v86, -v84, v83, v82
	v_fma_f32 v87, -v85, v83, v82
	v_cmp_ge_f32_e64 s[4:5], 0, v86
	s_nop 1
	v_cndmask_b32_e64 v83, v83, v84, s[4:5]
	v_cmp_lt_f32_e64 s[4:5], 0, v87
	s_nop 1
	v_cndmask_b32_e64 v83, v83, v85, s[4:5]
	v_mul_f32_e32 v84, 0x37800000, v83
	v_cndmask_b32_e32 v83, v83, v84, vcc
	v_cmp_class_f32_e32 vcc, v82, v159
	s_nop 1
	v_cndmask_b32_e32 v82, v83, v82, vcc
	v_div_scale_f32 v83, s[0:1], v82, v82, 1.0
	v_rcp_f32_e32 v84, v83
	v_div_scale_f32 v85, vcc, 1.0, v82, 1.0
	v_fma_f32 v86, -v83, v84, 1.0
	v_fmac_f32_e32 v84, v86, v84
	v_mul_f32_e32 v86, v85, v84
	v_fma_f32 v87, -v83, v86, v85
	v_fmac_f32_e32 v86, v87, v84
	v_fma_f32 v83, -v83, v86, v85
	v_div_fmas_f32 v83, v83, v84, v86
	v_div_fixup_f32 v82, v83, v82, 1.0
	v_pk_mul_f32 v[78:79], v[78:79], v[82:83] op_sel_hi:[1,0]
	v_pk_mul_f32 v[76:77], v[76:77], v[82:83] op_sel_hi:[1,0]
	v_pk_mul_f32 v[74:75], v[74:75], v[82:83] op_sel_hi:[1,0]
; __device__ __forceinline__ unsigned cvt_pk_bf16(float lo, float hi) { unsigned r; asm volatile("v_cvt_pk_bf16_f32 %0, %1, %2" : "=v"(r) : "v"(lo), "v"(hi)); return r; }
;     __device__ __forceinline__ void operator()(const f32x4 (&acc)[2][2][4][2], const Unit& u, int wr, int wc, int fr, int fq) const {
;         const int row0 = u.pm * BM + wr * 64 + fr, col0 = u.pn * BM + wc * 32 + 8 * fq;
; #pragma unroll
;         for (int ai = 0; ai < 2; ++ai)
; #pragma unroll
;             for (int m = 0; m < 4; ++m) {
;                 const int row = row0 + ai * HALF + m * 16; const float rs = 1.0f / sqrtf(__hip_atomic_load(ss2 + row, __ATOMIC_RELAXED, __HIP_MEMORY_SCOPE_AGENT) * (1.0f / 2048.0f) + EPSN);
;                 bf16_t* rowp = H + (size_t)row * DFF + col0;
; #pragma unroll
;                 for (int bj = 0; bj < 2; ++bj) {
;                     f32x4 v0 = acc[ai][bj][m][0] * rs, v1 = acc[ai][bj][m][1] * rs;
; #pragma unroll
;                     for (int j = 0; j < 4; ++j) { v0[j] = fmaxf(v0[j], 0.f); v0[j] *= v0[j]; v1[j] = fmaxf(v1[j], 0.f); v1[j] *= v1[j]; }
;                     u32x4 w; w.x = cvt_pk_bf16(v0[0], v0[1]); w.y = cvt_pk_bf16(v0[2], v0[3]); w.z = cvt_pk_bf16(v1[0], v1[1]); w.w = cvt_pk_bf16(v1[2], v1[3]);
;                     *(u32x4*)(rowp + bj * HALF) = w;
	v_pk_mul_f32 v[72:73], v[72:73], v[82:83] op_sel_hi:[1,0]
	v_pk_mul_f32 v[66:67], v[66:67], v[82:83] op_sel_hi:[1,0]
	v_pk_mul_f32 v[64:65], v[64:65], v[82:83] op_sel_hi:[1,0]
	v_pk_mul_f32 v[70:71], v[70:71], v[82:83] op_sel_hi:[1,0]
	v_pk_mul_f32 v[68:69], v[68:69], v[82:83] op_sel_hi:[1,0]
	v_max_f32_e32 v76, 0, v76
	v_max_f32_e32 v72, 0, v72
	v_max_f32_e32 v77, 0, v77
	v_max_f32_e32 v73, 0, v73
	v_max_f32_e32 v78, 0, v78
	v_max_f32_e32 v74, 0, v74
	v_max_f32_e32 v79, 0, v79
	v_max_f32_e32 v75, 0, v75
	v_max_f32_e32 v64, 0, v64
	v_max_f32_e32 v65, 0, v65
	v_max_f32_e32 v66, 0, v66
	v_max_f32_e32 v67, 0, v67
	v_max_f32_e32 v68, 0, v68
	v_max_f32_e32 v69, 0, v69
	v_max_f32_e32 v70, 0, v70
	v_max_f32_e32 v71, 0, v71
	v_mul_f32_e32 v76, v76, v76
	v_mul_f32_e32 v72, v72, v72
	v_mul_f32_e32 v77, v77, v77
	v_mul_f32_e32 v73, v73, v73
	v_mul_f32_e32 v78, v78, v78
	v_mul_f32_e32 v74, v74, v74
	v_mul_f32_e32 v79, v79, v79
	v_mul_f32_e32 v75, v75, v75
	v_mul_f32_e32 v82, v64, v64
	v_mul_f32_e32 v83, v65, v65
	v_mul_f32_e32 v84, v66, v66
	v_mul_f32_e32 v85, v67, v67
	v_cvt_pk_bf16_f32 v64, v76, v77
	v_cvt_pk_bf16_f32 v65, v78, v79
	v_cvt_pk_bf16_f32 v66, v72, v73
	v_cvt_pk_bf16_f32 v67, v74, v75
	v_mul_f32_e32 v68, v68, v68
	v_mul_f32_e32 v69, v69, v69
	v_mul_f32_e32 v70, v70, v70
	v_mul_f32_e32 v71, v71, v71
	global_store_dwordx4 v[80:81], v[64:67], off
	s_nop 1
	v_cvt_pk_bf16_f32 v64, v68, v69
	v_cvt_pk_bf16_f32 v65, v70, v71
	v_cvt_pk_bf16_f32 v66, v82, v83
	v_cvt_pk_bf16_f32 v67, v84, v85
	global_store_dwordx4 v[80:81], v[64:67], off offset:256
	s_nop 0
	s_nop 0
	v_fmamk_f32 v64, v231, 0x3a000000, v158
	v_mul_f32_e32 v65, 0x4f800000, v64
	v_cmp_gt_f32_e32 vcc, s75, v64
	s_nop 1
	v_cndmask_b32_e32 v66, v64, v65, vcc
	v_sqrt_f32_e32 v67, v66
	v_lshl_add_u64 v[64:65], v[146:147], 0, s[40:41]
	v_add_u32_e32 v68, -1, v67
	v_add_u32_e32 v69, 1, v67
	v_fma_f32 v70, -v68, v67, v66
	v_fma_f32 v71, -v69, v67, v66
	v_cmp_ge_f32_e64 s[4:5], 0, v70
	s_nop 1
	v_cndmask_b32_e64 v67, v67, v68, s[4:5]
	v_cmp_lt_f32_e64 s[4:5], 0, v71
	s_nop 1
	v_cndmask_b32_e64 v67, v67, v69, s[4:5]
	v_mul_f32_e32 v68, 0x37800000, v67
	v_cndmask_b32_e32 v67, v67, v68, vcc
	v_cmp_class_f32_e32 vcc, v66, v159
	s_nop 1
	v_cndmask_b32_e32 v68, v67, v66, vcc
	v_div_scale_f32 v69, s[0:1], v68, v68, 1.0
	v_rcp_f32_e32 v70, v69
	v_add_co_u32_e32 v66, vcc, s76, v146
	v_fma_f32 v72, -v69, v70, 1.0
	s_nop 0
	v_addc_co_u32_e32 v67, vcc, 0, v147, vcc
	v_div_scale_f32 v71, vcc, 1.0, v68, 1.0
	v_fmac_f32_e32 v70, v72, v70
	v_mul_f32_e32 v72, v71, v70
	v_fma_f32 v73, -v69, v72, v71
	v_fmac_f32_e32 v72, v73, v70
	v_fma_f32 v69, -v69, v72, v71
	v_div_fmas_f32 v69, v69, v70, v72
	v_div_fixup_f32 v68, v69, v68, 1.0
	v_pk_mul_f32 v[62:63], v[62:63], v[68:69] op_sel_hi:[1,0]
	v_pk_mul_f32 v[60:61], v[60:61], v[68:69] op_sel_hi:[1,0]
	v_pk_mul_f32 v[58:59], v[58:59], v[68:69] op_sel_hi:[1,0]
	v_pk_mul_f32 v[56:57], v[56:57], v[68:69] op_sel_hi:[1,0]
	v_pk_mul_f32 v[50:51], v[50:51], v[68:69] op_sel_hi:[1,0]
	v_pk_mul_f32 v[48:49], v[48:49], v[68:69] op_sel_hi:[1,0]
	v_pk_mul_f32 v[54:55], v[54:55], v[68:69] op_sel_hi:[1,0]
	v_pk_mul_f32 v[52:53], v[52:53], v[68:69] op_sel_hi:[1,0]
	v_max_f32_e32 v60, 0, v60
	v_max_f32_e32 v56, 0, v56
	v_max_f32_e32 v61, 0, v61
	v_max_f32_e32 v57, 0, v57
	v_max_f32_e32 v62, 0, v62
	v_max_f32_e32 v58, 0, v58
	v_max_f32_e32 v63, 0, v63
	v_max_f32_e32 v59, 0, v59
	v_max_f32_e32 v48, 0, v48
	v_max_f32_e32 v49, 0, v49
	v_max_f32_e32 v50, 0, v50
	v_max_f32_e32 v51, 0, v51
	v_max_f32_e32 v52, 0, v52
	v_max_f32_e32 v53, 0, v53
	v_max_f32_e32 v54, 0, v54
	v_max_f32_e32 v55, 0, v55
	v_mul_f32_e32 v60, v60, v60
	v_mul_f32_e32 v56, v56, v56
	v_mul_f32_e32 v61, v61, v61
	v_mul_f32_e32 v57, v57, v57
	v_mul_f32_e32 v62, v62, v62
	v_mul_f32_e32 v58, v58, v58
	v_mul_f32_e32 v63, v63, v63
	v_mul_f32_e32 v59, v59, v59
	v_mul_f32_e32 v68, v48, v48
	v_mul_f32_e32 v69, v49, v49
	v_mul_f32_e32 v70, v50, v50
	v_mul_f32_e32 v71, v51, v51
	v_cvt_pk_bf16_f32 v48, v60, v61
	v_cvt_pk_bf16_f32 v49, v62, v63
	v_cvt_pk_bf16_f32 v50, v56, v57
	v_cvt_pk_bf16_f32 v51, v58, v59
	v_mul_f32_e32 v52, v52, v52
	v_mul_f32_e32 v53, v53, v53
	v_mul_f32_e32 v54, v54, v54
	v_mul_f32_e32 v55, v55, v55
	global_store_dwordx4 v[66:67], v[48:51], off
	s_nop 1
	v_cvt_pk_bf16_f32 v48, v52, v53
	v_cvt_pk_bf16_f32 v49, v54, v55
	v_cvt_pk_bf16_f32 v50, v68, v69
	v_cvt_pk_bf16_f32 v51, v70, v71
	global_store_dwordx4 v[64:65], v[48:51], off offset:256
	s_nop 0
	s_nop 0
	v_fmamk_f32 v48, v232, 0x3a000000, v158
	v_mul_f32_e32 v49, 0x4f800000, v48
	v_cmp_gt_f32_e32 vcc, s75, v48
	s_nop 1
	v_cndmask_b32_e32 v50, v48, v49, vcc
	v_sqrt_f32_e32 v51, v50
	v_lshl_add_u64 v[48:49], v[146:147], 0, s[42:43]
	v_add_u32_e32 v52, -1, v51
	v_add_u32_e32 v53, 1, v51
	v_fma_f32 v54, -v52, v51, v50
	v_fma_f32 v55, -v53, v51, v50
	v_cmp_ge_f32_e64 s[4:5], 0, v54
	s_nop 1
	v_cndmask_b32_e64 v51, v51, v52, s[4:5]
	v_cmp_lt_f32_e64 s[4:5], 0, v55
	s_nop 1
	v_cndmask_b32_e64 v51, v51, v53, s[4:5]
	v_mul_f32_e32 v52, 0x37800000, v51
	v_cndmask_b32_e32 v51, v51, v52, vcc
	v_cmp_class_f32_e32 vcc, v50, v159
	s_nop 1
	v_cndmask_b32_e32 v52, v51, v50, vcc
	v_div_scale_f32 v53, s[0:1], v52, v52, 1.0
	v_rcp_f32_e32 v54, v53
	v_add_co_u32_e32 v50, vcc, s77, v146
	v_fma_f32 v56, -v53, v54, 1.0
	s_nop 0
	v_addc_co_u32_e32 v51, vcc, 0, v147, vcc
	v_div_scale_f32 v55, vcc, 1.0, v52, 1.0
	v_fmac_f32_e32 v54, v56, v54
	v_mul_f32_e32 v56, v55, v54
	v_fma_f32 v57, -v53, v56, v55
	v_fmac_f32_e32 v56, v57, v54
	v_fma_f32 v53, -v53, v56, v55
	v_div_fmas_f32 v53, v53, v54, v56
	v_div_fixup_f32 v52, v53, v52, 1.0
	v_pk_mul_f32 v[46:47], v[46:47], v[52:53] op_sel_hi:[1,0]
; __device__ __forceinline__ unsigned cvt_pk_bf16(float lo, float hi) { unsigned r; asm volatile("v_cvt_pk_bf16_f32 %0, %1, %2" : "=v"(r) : "v"(lo), "v"(hi)); return r; }
;     __device__ __forceinline__ void operator()(const f32x4 (&acc)[2][2][4][2], const Unit& u, int wr, int wc, int fr, int fq) const {
;         const int row0 = u.pm * BM + wr * 64 + fr, col0 = u.pn * BM + wc * 32 + 8 * fq;
; #pragma unroll
;         for (int ai = 0; ai < 2; ++ai)
; #pragma unroll
;             for (int m = 0; m < 4; ++m) {
;                 const int row = row0 + ai * HALF + m * 16; const float rs = 1.0f / sqrtf(__hip_atomic_load(ss2 + row, __ATOMIC_RELAXED, __HIP_MEMORY_SCOPE_AGENT) * (1.0f / 2048.0f) + EPSN);
;                 bf16_t* rowp = H + (size_t)row * DFF + col0;
; #pragma unroll
;                 for (int bj = 0; bj < 2; ++bj) {
;                     f32x4 v0 = acc[ai][bj][m][0] * rs, v1 = acc[ai][bj][m][1] * rs;
; #pragma unroll
;                     for (int j = 0; j < 4; ++j) { v0[j] = fmaxf(v0[j], 0.f); v0[j] *= v0[j]; v1[j] = fmaxf(v1[j], 0.f); v1[j] *= v1[j]; }
;                     u32x4 w; w.x = cvt_pk_bf16(v0[0], v0[1]); w.y = cvt_pk_bf16(v0[2], v0[3]); w.z = cvt_pk_bf16(v1[0], v1[1]); w.w = cvt_pk_bf16(v1[2], v1[3]);
;                     *(u32x4*)(rowp + bj * HALF) = w;
	v_pk_mul_f32 v[44:45], v[44:45], v[52:53] op_sel_hi:[1,0]
	v_pk_mul_f32 v[42:43], v[42:43], v[52:53] op_sel_hi:[1,0]
	v_pk_mul_f32 v[40:41], v[40:41], v[52:53] op_sel_hi:[1,0]
	v_pk_mul_f32 v[34:35], v[34:35], v[52:53] op_sel_hi:[1,0]
	v_pk_mul_f32 v[32:33], v[32:33], v[52:53] op_sel_hi:[1,0]
	v_pk_mul_f32 v[38:39], v[38:39], v[52:53] op_sel_hi:[1,0]
	v_pk_mul_f32 v[36:37], v[36:37], v[52:53] op_sel_hi:[1,0]
	v_max_f32_e32 v44, 0, v44
	v_max_f32_e32 v40, 0, v40
	v_max_f32_e32 v45, 0, v45
	v_max_f32_e32 v41, 0, v41
	v_max_f32_e32 v46, 0, v46
	v_max_f32_e32 v42, 0, v42
	v_max_f32_e32 v47, 0, v47
	v_max_f32_e32 v43, 0, v43
	v_max_f32_e32 v32, 0, v32
	v_max_f32_e32 v33, 0, v33
	v_max_f32_e32 v34, 0, v34
	v_max_f32_e32 v35, 0, v35
	v_max_f32_e32 v36, 0, v36
	v_max_f32_e32 v37, 0, v37
	v_max_f32_e32 v38, 0, v38
	v_max_f32_e32 v39, 0, v39
	v_mul_f32_e32 v44, v44, v44
	v_mul_f32_e32 v40, v40, v40
	v_mul_f32_e32 v45, v45, v45
	v_mul_f32_e32 v41, v41, v41
	v_mul_f32_e32 v46, v46, v46
	v_mul_f32_e32 v42, v42, v42
	v_mul_f32_e32 v47, v47, v47
	v_mul_f32_e32 v43, v43, v43
	v_mul_f32_e32 v52, v32, v32
	v_mul_f32_e32 v53, v33, v33
	v_mul_f32_e32 v54, v34, v34
	v_mul_f32_e32 v55, v35, v35
	v_cvt_pk_bf16_f32 v32, v44, v45
	v_cvt_pk_bf16_f32 v33, v46, v47
	v_cvt_pk_bf16_f32 v34, v40, v41
	v_cvt_pk_bf16_f32 v35, v42, v43
	v_mul_f32_e32 v36, v36, v36
	v_mul_f32_e32 v37, v37, v37
	v_mul_f32_e32 v38, v38, v38
	v_mul_f32_e32 v39, v39, v39
	global_store_dwordx4 v[50:51], v[32:35], off
	s_nop 1
	v_cvt_pk_bf16_f32 v32, v36, v37
	v_cvt_pk_bf16_f32 v33, v38, v39
	v_cvt_pk_bf16_f32 v34, v52, v53
	v_cvt_pk_bf16_f32 v35, v54, v55
	global_store_dwordx4 v[48:49], v[32:35], off offset:256
	s_nop 0
	s_nop 0
	v_fmamk_f32 v32, v233, 0x3a000000, v158
	v_mul_f32_e32 v33, 0x4f800000, v32
	v_cmp_gt_f32_e32 vcc, s75, v32
	s_nop 1
	v_cndmask_b32_e32 v34, v32, v33, vcc
	v_sqrt_f32_e32 v35, v34
	v_lshl_add_u64 v[32:33], v[146:147], 0, s[44:45]
	v_add_u32_e32 v36, -1, v35
	v_add_u32_e32 v37, 1, v35
	v_fma_f32 v38, -v36, v35, v34
	v_fma_f32 v39, -v37, v35, v34
	v_cmp_ge_f32_e64 s[4:5], 0, v38
	s_nop 1
	v_cndmask_b32_e64 v35, v35, v36, s[4:5]
	v_cmp_lt_f32_e64 s[4:5], 0, v39
	s_nop 1
	v_cndmask_b32_e64 v35, v35, v37, s[4:5]
	v_mul_f32_e32 v36, 0x37800000, v35
	v_cndmask_b32_e32 v35, v35, v36, vcc
	v_cmp_class_f32_e32 vcc, v34, v159
	s_nop 1
	v_cndmask_b32_e32 v36, v35, v34, vcc
	v_div_scale_f32 v37, s[0:1], v36, v36, 1.0
	v_rcp_f32_e32 v38, v37
	v_add_co_u32_e32 v34, vcc, s78, v146
	v_fma_f32 v40, -v37, v38, 1.0
	s_nop 0
	v_addc_co_u32_e32 v35, vcc, 0, v147, vcc
	v_div_scale_f32 v39, vcc, 1.0, v36, 1.0
	v_fmac_f32_e32 v38, v40, v38
	v_mul_f32_e32 v40, v39, v38
	v_fma_f32 v41, -v37, v40, v39
	v_fmac_f32_e32 v40, v41, v38
	v_fma_f32 v37, -v37, v40, v39
	v_div_fmas_f32 v37, v37, v38, v40
	v_div_fixup_f32 v36, v37, v36, 1.0
	v_pk_mul_f32 v[30:31], v[30:31], v[36:37] op_sel_hi:[1,0]
	v_pk_mul_f32 v[28:29], v[28:29], v[36:37] op_sel_hi:[1,0]
	v_pk_mul_f32 v[26:27], v[26:27], v[36:37] op_sel_hi:[1,0]
	v_pk_mul_f32 v[24:25], v[24:25], v[36:37] op_sel_hi:[1,0]
	v_pk_mul_f32 v[18:19], v[18:19], v[36:37] op_sel_hi:[1,0]
	v_pk_mul_f32 v[16:17], v[16:17], v[36:37] op_sel_hi:[1,0]
	v_pk_mul_f32 v[22:23], v[22:23], v[36:37] op_sel_hi:[1,0]
	v_pk_mul_f32 v[20:21], v[20:21], v[36:37] op_sel_hi:[1,0]
	v_max_f32_e32 v28, 0, v28
	v_max_f32_e32 v24, 0, v24
	v_max_f32_e32 v29, 0, v29
	v_max_f32_e32 v25, 0, v25
	v_max_f32_e32 v30, 0, v30
	v_max_f32_e32 v26, 0, v26
	v_max_f32_e32 v31, 0, v31
	v_max_f32_e32 v27, 0, v27
	v_max_f32_e32 v16, 0, v16
	v_max_f32_e32 v17, 0, v17
	v_max_f32_e32 v18, 0, v18
	v_max_f32_e32 v19, 0, v19
	v_max_f32_e32 v20, 0, v20
	v_max_f32_e32 v21, 0, v21
	v_max_f32_e32 v22, 0, v22
	v_max_f32_e32 v23, 0, v23
	v_mul_f32_e32 v28, v28, v28
; __device__ __forceinline__ unsigned cvt_pk_bf16(float lo, float hi) { unsigned r; asm volatile("v_cvt_pk_bf16_f32 %0, %1, %2" : "=v"(r) : "v"(lo), "v"(hi)); return r; }
; #define PG8_BAR __builtin_amdgcn_s_barrier()
;     __device__ __forceinline__ void operator()(const f32x4 (&acc)[2][2][4][2], const Unit& u, int wr, int wc, int fr, int fq) const {
;         const int row0 = u.pm * BM + wr * 64 + fr, col0 = u.pn * BM + wc * 32 + 8 * fq;
; #pragma unroll
;         for (int ai = 0; ai < 2; ++ai)
; #pragma unroll
;             for (int m = 0; m < 4; ++m) {
;                 const int row = row0 + ai * HALF + m * 16; const float rs = 1.0f / sqrtf(__hip_atomic_load(ss2 + row, __ATOMIC_RELAXED, __HIP_MEMORY_SCOPE_AGENT) * (1.0f / 2048.0f) + EPSN);
;                 bf16_t* rowp = H + (size_t)row * DFF + col0;
; #pragma unroll
;                 for (int bj = 0; bj < 2; ++bj) {
;                     f32x4 v0 = acc[ai][bj][m][0] * rs, v1 = acc[ai][bj][m][1] * rs;
; #pragma unroll
;                     for (int j = 0; j < 4; ++j) { v0[j] = fmaxf(v0[j], 0.f); v0[j] *= v0[j]; v1[j] = fmaxf(v1[j], 0.f); v1[j] *= v1[j]; }
;                     u32x4 w; w.x = cvt_pk_bf16(v0[0], v0[1]); w.y = cvt_pk_bf16(v0[2], v0[3]); w.z = cvt_pk_bf16(v1[0], v1[1]); w.w = cvt_pk_bf16(v1[2], v1[3]);
;                     *(u32x4*)(rowp + bj * HALF) = w;
; template <class Epi, class Sched, bool ALIGN_EPI = false, bool SP2 = false>
; __device__ __forceinline__ void gemm_phase(PG8_LAS unsigned char* lds, const Gemm g, const Sched& S, const Epi& E) {
;     ...
;         else if constexpr (!Epi::AFTER_DRAIN) { E(acc, cur, wr, wc, fr, fq); S.done(cur); }
;         if (!has_next) break;
;         if (!keep) {
; #pragma unroll
;         for (int a = 0; a < 2; ++a)
; #pragma unroll
;             for (int b = 0; b < 2; ++b)
; #pragma unroll
;                 for (int m = 0; m < 4; ++m)
; #pragma unroll
;                     for (int n = 0; n < 2; ++n) acc[a][b][m][n] = (f32x4){0.f, 0.f, 0.f, 0.f};
;         }
;         cur = nxt; cA = nA; cB = nB; ++ui;
;         if constexpr (ALIGN_EPI) { if (wr == 1) PG8_BAR; }
	v_mul_f32_e32 v24, v24, v24
	v_mul_f32_e32 v29, v29, v29
	v_mul_f32_e32 v25, v25, v25
	v_mul_f32_e32 v30, v30, v30
	v_mul_f32_e32 v26, v26, v26
	v_mul_f32_e32 v31, v31, v31
	v_mul_f32_e32 v27, v27, v27
	v_mul_f32_e32 v36, v16, v16
	v_mul_f32_e32 v37, v17, v17
	v_mul_f32_e32 v38, v18, v18
	v_mul_f32_e32 v39, v19, v19
	v_cvt_pk_bf16_f32 v16, v28, v29
	v_cvt_pk_bf16_f32 v17, v30, v31
	v_cvt_pk_bf16_f32 v18, v24, v25
	v_cvt_pk_bf16_f32 v19, v26, v27
	v_mul_f32_e32 v20, v20, v20
	v_mul_f32_e32 v21, v21, v21
	v_mul_f32_e32 v22, v22, v22
	v_mul_f32_e32 v23, v23, v23
	global_store_dwordx4 v[34:35], v[16:19], off
	s_nop 1
	v_cvt_pk_bf16_f32 v16, v20, v21
	v_cvt_pk_bf16_f32 v17, v22, v23
	v_cvt_pk_bf16_f32 v18, v36, v37
	v_cvt_pk_bf16_f32 v19, v38, v39
	global_store_dwordx4 v[32:33], v[16:19], off offset:256
	s_nop 0
	s_nop 0
	v_fmamk_f32 v16, v234, 0x3a000000, v158
	v_mul_f32_e32 v17, 0x4f800000, v16
	v_cmp_gt_f32_e32 vcc, s75, v16
	s_nop 1
	v_cndmask_b32_e32 v18, v16, v17, vcc
	v_sqrt_f32_e32 v19, v18
	v_lshl_add_u64 v[16:17], v[146:147], 0, s[46:47]
	v_add_u32_e32 v20, -1, v19
	v_add_u32_e32 v21, 1, v19
	v_fma_f32 v22, -v20, v19, v18
	v_fma_f32 v23, -v21, v19, v18
	v_cmp_ge_f32_e64 s[4:5], 0, v22
	s_nop 1
	v_cndmask_b32_e64 v19, v19, v20, s[4:5]
	v_cmp_lt_f32_e64 s[4:5], 0, v23
	s_nop 1
	v_cndmask_b32_e64 v19, v19, v21, s[4:5]
	v_mul_f32_e32 v20, 0x37800000, v19
	v_cndmask_b32_e32 v19, v19, v20, vcc
	v_cmp_class_f32_e32 vcc, v18, v159
	s_nop 1
	v_cndmask_b32_e32 v20, v19, v18, vcc
	v_div_scale_f32 v21, s[0:1], v20, v20, 1.0
	v_rcp_f32_e32 v22, v21
	v_add_co_u32_e32 v18, vcc, s79, v146
	v_fma_f32 v24, -v21, v22, 1.0
	s_nop 0
	v_addc_co_u32_e32 v19, vcc, 0, v147, vcc
	v_div_scale_f32 v23, vcc, 1.0, v20, 1.0
	v_fmac_f32_e32 v22, v24, v22
	v_mul_f32_e32 v24, v23, v22
	v_fma_f32 v25, -v21, v24, v23
	v_fmac_f32_e32 v24, v25, v22
	v_fma_f32 v21, -v21, v24, v23
	v_div_fmas_f32 v21, v21, v22, v24
	v_div_fixup_f32 v20, v21, v20, 1.0
	v_pk_mul_f32 v[14:15], v[14:15], v[20:21] op_sel_hi:[1,0]
	v_pk_mul_f32 v[12:13], v[12:13], v[20:21] op_sel_hi:[1,0]
	v_pk_mul_f32 v[10:11], v[10:11], v[20:21] op_sel_hi:[1,0]
	v_pk_mul_f32 v[8:9], v[8:9], v[20:21] op_sel_hi:[1,0]
	v_pk_mul_f32 v[2:3], v[2:3], v[20:21] op_sel_hi:[1,0]
	v_pk_mul_f32 v[0:1], v[0:1], v[20:21] op_sel_hi:[1,0]
	v_pk_mul_f32 v[6:7], v[6:7], v[20:21] op_sel_hi:[1,0]
	v_pk_mul_f32 v[4:5], v[4:5], v[20:21] op_sel_hi:[1,0]
	v_max_f32_e32 v12, 0, v12
	v_max_f32_e32 v8, 0, v8
	v_max_f32_e32 v13, 0, v13
	v_max_f32_e32 v9, 0, v9
	v_max_f32_e32 v14, 0, v14
	v_max_f32_e32 v10, 0, v10
	v_max_f32_e32 v15, 0, v15
	v_max_f32_e32 v11, 0, v11
	v_max_f32_e32 v0, 0, v0
	v_max_f32_e32 v1, 0, v1
	v_max_f32_e32 v2, 0, v2
	v_max_f32_e32 v3, 0, v3
	s_andn2_b64 vcc, exec, s[2:3]
	v_max_f32_e32 v4, 0, v4
	v_max_f32_e32 v5, 0, v5
	v_max_f32_e32 v6, 0, v6
	v_max_f32_e32 v7, 0, v7
	v_mul_f32_e32 v12, v12, v12
	v_mul_f32_e32 v8, v8, v8
	v_mul_f32_e32 v13, v13, v13
	v_mul_f32_e32 v9, v9, v9
	v_mul_f32_e32 v14, v14, v14
	v_mul_f32_e32 v10, v10, v10
	v_mul_f32_e32 v15, v15, v15
	v_mul_f32_e32 v11, v11, v11
	v_mul_f32_e32 v20, v0, v0
	v_mul_f32_e32 v21, v1, v1
	v_mul_f32_e32 v22, v2, v2
	v_mul_f32_e32 v23, v3, v3
	v_cvt_pk_bf16_f32 v0, v12, v13
	v_cvt_pk_bf16_f32 v1, v14, v15
	v_cvt_pk_bf16_f32 v2, v8, v9
	v_cvt_pk_bf16_f32 v3, v10, v11
	s_mov_b64 s[2:3], -1
	v_mul_f32_e32 v4, v4, v4
	v_mul_f32_e32 v5, v5, v5
	v_mul_f32_e32 v6, v6, v6
	v_mul_f32_e32 v7, v7, v7
	global_store_dwordx4 v[18:19], v[0:3], off
	s_nop 1
	v_cvt_pk_bf16_f32 v0, v4, v5
	v_cvt_pk_bf16_f32 v1, v6, v7
	v_cvt_pk_bf16_f32 v2, v20, v21
	v_cvt_pk_bf16_f32 v3, v22, v23
	global_store_dwordx4 v[16:17], v[0:3], off offset:256
	s_cbranch_vccnz .LBB0_853
	s_andn2_b64 vcc, exec, s[20:21]
	s_cbranch_vccnz .LBB0_852
	s_barrier
	s_branch .LBB0_852

;     __host__ __device__ bool next(int i, Unit& u) const { if (!StaticOrder::next(i >> 1, u)) return false; u.kh = i & 1; u.slot = i >> 1; return true; }
;     __host__ __device__ bool next(int i, Unit& u) const {
;         const long L = (long)i * G + c; if (L >= nwg) return false;
;         int wgid = (int)L; { const int q = nwg / NXCD, r = nwg % NXCD, xcd = wgid % NXCD, off = wgid / NXCD; wgid = (xcd < r ? xcd * (q + 1) : r * (q + 1) + (xcd - r) * q) + off; }
;         const int nig = wgm * nN, gid = wgid / nig, fm = gid * wgm, gsz = (nM - fm) < wgm ? (nM - fm) : wgm;
;     __device__ __forceinline__ void operator()(const f32x4 (&acc)[2][2][4][2], const Unit& u, int wr, int wc, int fr, int fq) const {
;     ...
;                 const int row = row0 + ai * HALF + m * 16; const float rs = 1.0f / sqrtf(__hip_atomic_load(ss2 + row, __ATOMIC_RELAXED, __HIP_MEMORY_SCOPE_AGENT) * (1.0f / 2048.0f) + EPSN);
.LBB0_1054:
	v_lshl_add_u32 v236, s6, 8, v152
	v_ashrrev_i32_e32 v237, 31, v236
	v_lshl_add_u64 v[236:237], v[236:237], 2, s[24:25]
	global_load_dword v238, v[236:237], off sc1
	global_load_dword v239, v[236:237], off offset:64 sc1
	global_load_dword v240, v[236:237], off offset:128 sc1
	global_load_dword v241, v[236:237], off offset:192 sc1
	global_load_dword v242, v[236:237], off offset:512 sc1
	global_load_dword v243, v[236:237], off offset:576 sc1
	global_load_dword v244, v[236:237], off offset:640 sc1
	global_load_dword v245, v[236:237], off offset:704 sc1
	s_nop 0
	s_add_i32 s67, s67, 1
	s_mul_i32 s1, s67, s70
	s_mul_hi_u32 s4, s67, s71
	s_add_i32 s4, s4, s1
	s_mul_i32 s1, s67, s71
	s_add_u32 s52, s1, s12
	s_addc_u32 s53, s4, s13
	v_cmp_gt_i64_e32 vcc, s[52:53], v[142:143]
	v_cmp_lt_i64_e64 s[4:5], s[52:53], v[140:141]
	s_cbranch_vccnz .LBB0_1060
	s_ashr_i32 s1, s52, 31
	s_lshr_b32 s1, s1, 29
	s_add_i32 s1, s52, s1
	s_and_b32 s7, s1, -8
	s_sub_i32 s7, s52, s7
	s_cmp_gt_i32 s7, -1
	s_mov_b64 s[48:49], -1
	s_cbranch_scc0 .LBB0_1057
	s_lshl_b32 s50, s7, 7
	s_mov_b64 s[48:49], 0

;     __host__ __device__ bool next(int i, Unit& u) const { if (!StaticOrder::next(i >> 1, u)) return false; u.kh = i & 1; u.slot = i >> 1; return true; }
; template <class Epi, class Sched, bool ALIGN_EPI = false, bool SP2 = false>
; __device__ __forceinline__ void gemm_phase(PG8_LAS unsigned char* lds, const Gemm g, const Sched& S, const Epi& E) {
;     ...
;         const bool has_next = S.next(ui + 1, nxt);
;         const char* nA = has_next ? (const char*)g.A + (size_t)nxt.pm * tstep + nxt.kh * khstep : cA; const char* nB = has_next ? (const char*)g.Bt + (size_t)nxt.pn * tstep + nxt.kh * khstep : cB;
;         for (int t = 0; t < nt; t += 2) {
;             const bool last = (t == nt - 2);
;             const char* a1 = cA + (size_t)(t + 1) * kstep;
;             const char* a2 = last ? nA : cA + (size_t)(t + 2) * kstep; const char* b2 = last ? nB : cB + (size_t)(t + 2) * kstep;
;     ...
; #pragma unroll
;         for (int a = 0; a < 2; ++a)
; #pragma unroll
;             for (int b = 0; b < 2; ++b)
; #pragma unroll
;                 for (int m = 0; m < 4; ++m)
; #pragma unroll
;                     for (int n = 0; n < 2; ++n) acc[a][b][m][n] = (f32x4){0.f, 0.f, 0.f, 0.f};
;         }
;         cur = nxt; cA = nA; cB = nB; ++ui;
.LBB0_1060:
	s_ashr_i32 s51, s50, 31
	s_lshl_b64 s[52:53], s[50:51], 20
	s_add_u32 s52, s20, s52
	s_addc_u32 s53, s21, s53
	s_and_b64 s[54:55], s[4:5], exec
	s_cselect_b32 s1, s53, s57
	s_cselect_b32 s7, s52, s56
	s_ashr_i32 s49, s48, 31
	s_lshl_b64 s[54:55], s[48:49], 20
	s_add_u32 s54, s8, s54
	s_addc_u32 s55, s9, s55
	s_and_b64 s[60:61], s[4:5], exec
	s_cselect_b32 s49, s55, s59
	s_cselect_b32 s51, s54, s58
	s_add_u32 s56, s56, 0x80080
	s_addc_u32 s57, s57, 0
	s_add_u32 s82, s58, 0x100
	v_mov_b32_e32 v0, 0
	s_addc_u32 s83, s59, 0
	s_mov_b32 s84, -2
	v_mov_b32_e32 v1, v0
	v_mov_b32_e32 v2, v0
	v_mov_b32_e32 v3, v0
	v_mov_b32_e32 v4, v0
	v_mov_b32_e32 v5, v0
	v_mov_b32_e32 v6, v0
	v_mov_b32_e32 v7, v0
	v_mov_b32_e32 v16, v0
	v_mov_b32_e32 v17, v0
	v_mov_b32_e32 v18, v0
	v_mov_b32_e32 v19, v0
	v_mov_b32_e32 v20, v0
	v_mov_b32_e32 v21, v0
	v_mov_b32_e32 v22, v0
	v_mov_b32_e32 v23, v0
	v_mov_b32_e32 v32, v0
	v_mov_b32_e32 v33, v0
	v_mov_b32_e32 v34, v0
	v_mov_b32_e32 v35, v0
	v_mov_b32_e32 v36, v0
	v_mov_b32_e32 v37, v0
	v_mov_b32_e32 v38, v0
	v_mov_b32_e32 v39, v0
	v_mov_b32_e32 v48, v0
	v_mov_b32_e32 v49, v0
	v_mov_b32_e32 v50, v0
	v_mov_b32_e32 v51, v0
	v_mov_b32_e32 v52, v0
	v_mov_b32_e32 v53, v0
	v_mov_b32_e32 v54, v0
	v_mov_b32_e32 v55, v0
	v_mov_b32_e32 v8, v0
	v_mov_b32_e32 v9, v0
	v_mov_b32_e32 v10, v0
	v_mov_b32_e32 v11, v0
	v_mov_b32_e32 v12, v0
	v_mov_b32_e32 v13, v0
	v_mov_b32_e32 v14, v0
	v_mov_b32_e32 v15, v0
	s_waitcnt vmcnt(24)
	v_mov_b32_e32 v24, v0
	v_mov_b32_e32 v25, v0
	v_mov_b32_e32 v26, v0
	v_mov_b32_e32 v27, v0
	v_mov_b32_e32 v28, v0
	v_mov_b32_e32 v29, v0
	v_mov_b32_e32 v30, v0
	v_mov_b32_e32 v31, v0
	v_mov_b32_e32 v40, v0
	v_mov_b32_e32 v41, v0
	v_mov_b32_e32 v42, v0
	v_mov_b32_e32 v43, v0
	v_mov_b32_e32 v44, v0
	v_mov_b32_e32 v45, v0
	v_mov_b32_e32 v46, v0
	v_mov_b32_e32 v47, v0
	v_mov_b32_e32 v56, v0
	v_mov_b32_e32 v57, v0
	v_mov_b32_e32 v58, v0
	v_mov_b32_e32 v59, v0
	v_mov_b32_e32 v60, v0
	v_mov_b32_e32 v61, v0
	v_mov_b32_e32 v62, v0
	v_mov_b32_e32 v63, v0
	v_mov_b32_e32 v64, v0
	v_mov_b32_e32 v65, v0
	v_mov_b32_e32 v66, v0
	v_mov_b32_e32 v67, v0
	v_mov_b32_e32 v68, v0
	v_mov_b32_e32 v69, v0
	v_mov_b32_e32 v70, v0
	v_mov_b32_e32 v71, v0
	v_mov_b32_e32 v80, v0
	v_mov_b32_e32 v81, v0
	v_mov_b32_e32 v82, v0
	v_mov_b32_e32 v83, v0
	v_mov_b32_e32 v84, v0
	v_mov_b32_e32 v85, v0
	v_mov_b32_e32 v86, v0
	v_mov_b32_e32 v87, v0
	v_mov_b32_e32 v96, v0
	v_mov_b32_e32 v97, v0
	v_mov_b32_e32 v98, v0
	v_mov_b32_e32 v99, v0
	v_mov_b32_e32 v100, v0
	v_mov_b32_e32 v101, v0
	v_mov_b32_e32 v102, v0
	v_mov_b32_e32 v103, v0
	v_mov_b32_e32 v112, v0
	v_mov_b32_e32 v113, v0
	v_mov_b32_e32 v114, v0
	v_mov_b32_e32 v115, v0
	v_mov_b32_e32 v116, v0
	v_mov_b32_e32 v117, v0
	v_mov_b32_e32 v118, v0
	v_mov_b32_e32 v119, v0
	v_mov_b32_e32 v72, v0
	v_mov_b32_e32 v73, v0
	v_mov_b32_e32 v74, v0
	v_mov_b32_e32 v75, v0
	v_mov_b32_e32 v76, v0
	v_mov_b32_e32 v77, v0
	v_mov_b32_e32 v78, v0
	v_mov_b32_e32 v79, v0
	v_mov_b32_e32 v88, v0
	v_mov_b32_e32 v89, v0
	v_mov_b32_e32 v90, v0
	v_mov_b32_e32 v91, v0
	v_mov_b32_e32 v92, v0
	v_mov_b32_e32 v93, v0
	v_mov_b32_e32 v94, v0
	v_mov_b32_e32 v95, v0
	v_mov_b32_e32 v104, v0
	v_mov_b32_e32 v105, v0
	v_mov_b32_e32 v106, v0
	v_mov_b32_e32 v107, v0
	v_mov_b32_e32 v108, v0
	v_mov_b32_e32 v109, v0
	v_mov_b32_e32 v110, v0
	v_mov_b32_e32 v111, v0
	v_mov_b32_e32 v120, v0
	v_mov_b32_e32 v121, v0
	v_mov_b32_e32 v122, v0
	v_mov_b32_e32 v123, v0
	v_mov_b32_e32 v124, v0
	v_mov_b32_e32 v125, v0
	v_mov_b32_e32 v126, v0
	v_mov_b32_e32 v127, v0

; __device__ __forceinline__ unsigned cvt_pk_bf16(float lo, float hi) { unsigned r; asm volatile("v_cvt_pk_bf16_f32 %0, %1, %2" : "=v"(r) : "v"(lo), "v"(hi)); return r; }
;     __device__ __forceinline__ void operator()(const f32x4 (&acc)[2][2][4][2], const Unit& u, int wr, int wc, int fr, int fq) const {
;         const int row0 = u.pm * BM + wr * 64 + fr, col0 = u.pn * BM + wc * 32 + 8 * fq;
; #pragma unroll
;         for (int ai = 0; ai < 2; ++ai)
; #pragma unroll
;             for (int m = 0; m < 4; ++m) {
;                 const int row = row0 + ai * HALF + m * 16; const float rs = 1.0f / sqrtf(__hip_atomic_load(ss2 + row, __ATOMIC_RELAXED, __HIP_MEMORY_SCOPE_AGENT) * (1.0f / 2048.0f) + EPSN);
;                 bf16_t* rowp = H + (size_t)row * DFF + col0;
; #pragma unroll
;                 for (int bj = 0; bj < 2; ++bj) {
;                     f32x4 v0 = acc[ai][bj][m][0] * rs, v1 = acc[ai][bj][m][1] * rs;
; #pragma unroll
;                     for (int j = 0; j < 4; ++j) { v0[j] = fmaxf(v0[j], 0.f); v0[j] *= v0[j]; v1[j] = fmaxf(v1[j], 0.f); v1[j] *= v1[j]; }
;                     u32x4 w; w.x = cvt_pk_bf16(v0[0], v0[1]); w.y = cvt_pk_bf16(v0[2], v0[3]); w.z = cvt_pk_bf16(v1[0], v1[1]); w.w = cvt_pk_bf16(v1[2], v1[3]);
;                     *(u32x4*)(rowp + bj * HALF) = w;
.LBB0_1064:
	v_lshl_add_u32 v150, s6, 8, v152
	v_ashrrev_i32_e32 v151, 31, v150
	v_lshl_add_u64 v[144:145], v[150:151], 2, s[24:25]
	v_mov_b32_e32 v161, v238
	v_mov_b32_e32 v228, v239
	v_mov_b32_e32 v229, v240
	v_mov_b32_e32 v230, v241
	v_mov_b32_e32 v231, v242
	v_mov_b32_e32 v232, v243
	v_mov_b32_e32 v233, v244
	v_mov_b32_e32 v234, v245
	v_lshl_or_b32 v146, s0, 8, v154
	v_ashrrev_i32_e32 v147, 31, v146
	v_lshlrev_b64 v[148:149], 1, v[146:147]
	v_lshlrev_b64 v[164:165], 14, v[150:151]
	v_or_b32_e32 v162, 16, v150
	v_ashrrev_i32_e32 v163, 31, v162
	s_nop 0
	v_fmamk_f32 v146, v161, 0x3a000000, v158
	v_mul_f32_e32 v147, 0x4f800000, v146
	v_cmp_gt_f32_e32 vcc, s77, v146
	s_nop 1
	v_cndmask_b32_e32 v151, v146, v147, vcc
	v_sqrt_f32_e32 v161, v151
	v_lshl_add_u64 v[146:147], s[10:11], 0, v[164:165]
	v_lshl_add_u64 v[146:147], v[146:147], 0, v[148:149]
	v_lshl_add_u64 v[164:165], v[162:163], 2, s[24:25]
	v_add_u32_e32 v166, -1, v161
	v_add_u32_e32 v167, 1, v161
	v_fma_f32 v168, -v166, v161, v151
	v_fma_f32 v169, -v167, v161, v151
	v_cmp_ge_f32_e64 s[6:7], 0, v168
	s_nop 1
	v_cndmask_b32_e64 v161, v161, v166, s[6:7]
	v_cmp_lt_f32_e64 s[6:7], 0, v169
	s_nop 1
	v_cndmask_b32_e64 v161, v161, v167, s[6:7]
	v_mul_f32_e32 v166, 0x37800000, v161
	v_cndmask_b32_e32 v161, v161, v166, vcc
	v_cmp_class_f32_e32 vcc, v151, v159
	s_nop 1
	v_cndmask_b32_e32 v151, v161, v151, vcc
	v_div_scale_f32 v161, s[0:1], v151, v151, 1.0
	v_rcp_f32_e32 v166, v161
	v_div_scale_f32 v167, vcc, 1.0, v151, 1.0
	v_fma_f32 v168, -v161, v166, 1.0
	v_fmac_f32_e32 v166, v168, v166
	v_mul_f32_e32 v168, v167, v166
	v_fma_f32 v169, -v161, v168, v167
	v_fmac_f32_e32 v168, v169, v166
	v_fma_f32 v161, -v161, v168, v167
	v_div_fmas_f32 v161, v161, v166, v168
	v_div_fixup_f32 v166, v161, v151, 1.0
	v_pk_mul_f32 v[126:127], v[126:127], v[166:167] op_sel_hi:[1,0]
	v_pk_mul_f32 v[124:125], v[124:125], v[166:167] op_sel_hi:[1,0]
	v_pk_mul_f32 v[122:123], v[122:123], v[166:167] op_sel_hi:[1,0]
	v_pk_mul_f32 v[120:121], v[120:121], v[166:167] op_sel_hi:[1,0]
	v_pk_mul_f32 v[114:115], v[114:115], v[166:167] op_sel_hi:[1,0]
	v_pk_mul_f32 v[112:113], v[112:113], v[166:167] op_sel_hi:[1,0]
	v_pk_mul_f32 v[118:119], v[118:119], v[166:167] op_sel_hi:[1,0]
	v_pk_mul_f32 v[116:117], v[116:117], v[166:167] op_sel_hi:[1,0]
	v_max_f32_e32 v124, 0, v124
	v_max_f32_e32 v120, 0, v120
	v_max_f32_e32 v125, 0, v125
	v_max_f32_e32 v121, 0, v121
	v_max_f32_e32 v126, 0, v126
	v_max_f32_e32 v122, 0, v122
	v_max_f32_e32 v127, 0, v127
	v_max_f32_e32 v123, 0, v123
	v_max_f32_e32 v112, 0, v112
	v_max_f32_e32 v113, 0, v113
	v_max_f32_e32 v114, 0, v114
	v_max_f32_e32 v115, 0, v115
	v_max_f32_e32 v116, 0, v116
	v_max_f32_e32 v117, 0, v117
	v_max_f32_e32 v118, 0, v118
	v_max_f32_e32 v119, 0, v119
	v_mul_f32_e32 v124, v124, v124
	v_mul_f32_e32 v120, v120, v120
	v_mul_f32_e32 v125, v125, v125
	v_mul_f32_e32 v121, v121, v121
	v_mul_f32_e32 v126, v126, v126
	v_mul_f32_e32 v122, v122, v122
	v_mul_f32_e32 v127, v127, v127
	v_mul_f32_e32 v123, v123, v123
	v_mul_f32_e32 v151, v112, v112
	v_mul_f32_e32 v161, v113, v113
	v_mul_f32_e32 v166, v114, v114
	v_mul_f32_e32 v167, v115, v115
	v_cvt_pk_bf16_f32 v112, v124, v125
	v_cvt_pk_bf16_f32 v113, v126, v127
	v_cvt_pk_bf16_f32 v114, v120, v121
	v_cvt_pk_bf16_f32 v115, v122, v123
	v_mul_f32_e32 v116, v116, v116
	v_mul_f32_e32 v117, v117, v117
	v_mul_f32_e32 v118, v118, v118
	v_mul_f32_e32 v119, v119, v119
	global_store_dwordx4 v[146:147], v[112:115], off
	s_nop 1
	v_cvt_pk_bf16_f32 v112, v116, v117
	v_cvt_pk_bf16_f32 v113, v118, v119
	v_cvt_pk_bf16_f32 v114, v151, v161
	v_cvt_pk_bf16_f32 v115, v166, v167
	global_store_dwordx4 v[146:147], v[112:115], off offset:256
	s_nop 0
	s_nop 0
	v_or_b32_e32 v112, 32, v150
	v_ashrrev_i32_e32 v113, 31, v112
	v_lshl_add_u64 v[116:117], v[112:113], 2, s[24:25]
	s_nop 0
	v_fmamk_f32 v114, v228, 0x3a000000, v158
	v_mul_f32_e32 v115, 0x4f800000, v114
	v_cmp_gt_f32_e32 vcc, s77, v114
	s_nop 1
	v_cndmask_b32_e32 v118, v114, v115, vcc
	v_sqrt_f32_e32 v119, v118
	v_lshlrev_b64 v[114:115], 14, v[162:163]
	v_lshl_add_u64 v[114:115], s[10:11], 0, v[114:115]
	v_lshl_add_u64 v[114:115], v[114:115], 0, v[148:149]
	v_add_u32_e32 v120, -1, v119
	v_add_u32_e32 v121, 1, v119
	v_fma_f32 v122, -v120, v119, v118
	v_fma_f32 v123, -v121, v119, v118
	v_cmp_ge_f32_e64 s[6:7], 0, v122
	s_nop 1
	v_cndmask_b32_e64 v119, v119, v120, s[6:7]
	v_cmp_lt_f32_e64 s[6:7], 0, v123
	s_nop 1
	v_cndmask_b32_e64 v119, v119, v121, s[6:7]
	v_mul_f32_e32 v120, 0x37800000, v119
	v_cndmask_b32_e32 v119, v119, v120, vcc
	v_cmp_class_f32_e32 vcc, v118, v159
	s_nop 1
	v_cndmask_b32_e32 v118, v119, v118, vcc
	v_div_scale_f32 v119, s[0:1], v118, v118, 1.0
	v_rcp_f32_e32 v120, v119
	v_div_scale_f32 v121, vcc, 1.0, v118, 1.0
	v_fma_f32 v122, -v119, v120, 1.0
	v_fmac_f32_e32 v120, v122, v120
	v_mul_f32_e32 v122, v121, v120
	v_fma_f32 v123, -v119, v122, v121
	v_fmac_f32_e32 v122, v123, v120
	v_fma_f32 v119, -v119, v122, v121
	v_div_fmas_f32 v119, v119, v120, v122
	v_div_fixup_f32 v118, v119, v118, 1.0
	v_pk_mul_f32 v[110:111], v[110:111], v[118:119] op_sel_hi:[1,0]
	v_pk_mul_f32 v[108:109], v[108:109], v[118:119] op_sel_hi:[1,0]
	v_pk_mul_f32 v[106:107], v[106:107], v[118:119] op_sel_hi:[1,0]
	v_pk_mul_f32 v[104:105], v[104:105], v[118:119] op_sel_hi:[1,0]
	v_pk_mul_f32 v[98:99], v[98:99], v[118:119] op_sel_hi:[1,0]
	v_pk_mul_f32 v[96:97], v[96:97], v[118:119] op_sel_hi:[1,0]
	v_pk_mul_f32 v[102:103], v[102:103], v[118:119] op_sel_hi:[1,0]
	v_pk_mul_f32 v[100:101], v[100:101], v[118:119] op_sel_hi:[1,0]
	v_max_f32_e32 v108, 0, v108
	v_max_f32_e32 v104, 0, v104
	v_max_f32_e32 v109, 0, v109
	v_max_f32_e32 v105, 0, v105
; __device__ __forceinline__ unsigned cvt_pk_bf16(float lo, float hi) { unsigned r; asm volatile("v_cvt_pk_bf16_f32 %0, %1, %2" : "=v"(r) : "v"(lo), "v"(hi)); return r; }
;     __device__ __forceinline__ void operator()(const f32x4 (&acc)[2][2][4][2], const Unit& u, int wr, int wc, int fr, int fq) const {
;         const int row0 = u.pm * BM + wr * 64 + fr, col0 = u.pn * BM + wc * 32 + 8 * fq;
; #pragma unroll
;         for (int ai = 0; ai < 2; ++ai)
; #pragma unroll
;             for (int m = 0; m < 4; ++m) {
;                 const int row = row0 + ai * HALF + m * 16; const float rs = 1.0f / sqrtf(__hip_atomic_load(ss2 + row, __ATOMIC_RELAXED, __HIP_MEMORY_SCOPE_AGENT) * (1.0f / 2048.0f) + EPSN);
;                 bf16_t* rowp = H + (size_t)row * DFF + col0;
; #pragma unroll
;                 for (int bj = 0; bj < 2; ++bj) {
;                     f32x4 v0 = acc[ai][bj][m][0] * rs, v1 = acc[ai][bj][m][1] * rs;
; #pragma unroll
;                     for (int j = 0; j < 4; ++j) { v0[j] = fmaxf(v0[j], 0.f); v0[j] *= v0[j]; v1[j] = fmaxf(v1[j], 0.f); v1[j] *= v1[j]; }
;                     u32x4 w; w.x = cvt_pk_bf16(v0[0], v0[1]); w.y = cvt_pk_bf16(v0[2], v0[3]); w.z = cvt_pk_bf16(v1[0], v1[1]); w.w = cvt_pk_bf16(v1[2], v1[3]);
;                     *(u32x4*)(rowp + bj * HALF) = w;
	v_max_f32_e32 v110, 0, v110
	v_max_f32_e32 v106, 0, v106
	v_max_f32_e32 v111, 0, v111
	v_max_f32_e32 v107, 0, v107
	v_max_f32_e32 v96, 0, v96
	v_max_f32_e32 v97, 0, v97
	v_max_f32_e32 v98, 0, v98
	v_max_f32_e32 v99, 0, v99
	v_max_f32_e32 v100, 0, v100
	v_max_f32_e32 v101, 0, v101
	v_max_f32_e32 v102, 0, v102
	v_max_f32_e32 v103, 0, v103
	v_mul_f32_e32 v108, v108, v108
	v_mul_f32_e32 v104, v104, v104
	v_mul_f32_e32 v109, v109, v109
	v_mul_f32_e32 v105, v105, v105
	v_mul_f32_e32 v110, v110, v110
	v_mul_f32_e32 v106, v106, v106
	v_mul_f32_e32 v111, v111, v111
	v_mul_f32_e32 v107, v107, v107
	v_mul_f32_e32 v118, v96, v96
	v_mul_f32_e32 v119, v97, v97
	v_mul_f32_e32 v120, v98, v98
	v_mul_f32_e32 v121, v99, v99
	v_cvt_pk_bf16_f32 v96, v108, v109
	v_cvt_pk_bf16_f32 v97, v110, v111
	v_cvt_pk_bf16_f32 v98, v104, v105
	v_cvt_pk_bf16_f32 v99, v106, v107
	v_mul_f32_e32 v100, v100, v100
	v_mul_f32_e32 v101, v101, v101
	v_mul_f32_e32 v102, v102, v102
	v_mul_f32_e32 v103, v103, v103
	global_store_dwordx4 v[114:115], v[96:99], off
	s_nop 1
	v_cvt_pk_bf16_f32 v96, v100, v101
	v_cvt_pk_bf16_f32 v97, v102, v103
	v_cvt_pk_bf16_f32 v98, v118, v119
	v_cvt_pk_bf16_f32 v99, v120, v121
	global_store_dwordx4 v[114:115], v[96:99], off offset:256
	s_nop 0
	s_nop 0
	v_or_b32_e32 v96, 48, v150
	v_ashrrev_i32_e32 v97, 31, v96
	v_lshl_add_u64 v[100:101], v[96:97], 2, s[24:25]
	s_nop 0
	v_fmamk_f32 v98, v229, 0x3a000000, v158
	v_mul_f32_e32 v99, 0x4f800000, v98
	v_cmp_gt_f32_e32 vcc, s77, v98
	s_nop 1
	v_cndmask_b32_e32 v102, v98, v99, vcc
	v_sqrt_f32_e32 v103, v102
	v_lshlrev_b64 v[98:99], 14, v[112:113]
	v_lshl_add_u64 v[98:99], s[10:11], 0, v[98:99]
	v_lshl_add_u64 v[98:99], v[98:99], 0, v[148:149]
	v_add_u32_e32 v104, -1, v103
	v_add_u32_e32 v105, 1, v103
	v_fma_f32 v106, -v104, v103, v102
	v_fma_f32 v107, -v105, v103, v102
	v_cmp_ge_f32_e64 s[6:7], 0, v106
	s_nop 1
	v_cndmask_b32_e64 v103, v103, v104, s[6:7]
	v_cmp_lt_f32_e64 s[6:7], 0, v107
	s_nop 1
	v_cndmask_b32_e64 v103, v103, v105, s[6:7]
	v_mul_f32_e32 v104, 0x37800000, v103
	v_cndmask_b32_e32 v103, v103, v104, vcc
	v_cmp_class_f32_e32 vcc, v102, v159
	s_nop 1
	v_cndmask_b32_e32 v102, v103, v102, vcc
	v_div_scale_f32 v103, s[0:1], v102, v102, 1.0
	v_rcp_f32_e32 v104, v103
	v_div_scale_f32 v105, vcc, 1.0, v102, 1.0
	v_fma_f32 v106, -v103, v104, 1.0
	v_fmac_f32_e32 v104, v106, v104
	v_mul_f32_e32 v106, v105, v104
	v_fma_f32 v107, -v103, v106, v105
	v_fmac_f32_e32 v106, v107, v104
	v_fma_f32 v103, -v103, v106, v105
	v_div_fmas_f32 v103, v103, v104, v106
	v_div_fixup_f32 v102, v103, v102, 1.0
	v_pk_mul_f32 v[94:95], v[94:95], v[102:103] op_sel_hi:[1,0]
	v_pk_mul_f32 v[92:93], v[92:93], v[102:103] op_sel_hi:[1,0]
	v_pk_mul_f32 v[90:91], v[90:91], v[102:103] op_sel_hi:[1,0]
	v_pk_mul_f32 v[88:89], v[88:89], v[102:103] op_sel_hi:[1,0]
	v_pk_mul_f32 v[82:83], v[82:83], v[102:103] op_sel_hi:[1,0]
	v_pk_mul_f32 v[80:81], v[80:81], v[102:103] op_sel_hi:[1,0]
	v_pk_mul_f32 v[86:87], v[86:87], v[102:103] op_sel_hi:[1,0]
	v_pk_mul_f32 v[84:85], v[84:85], v[102:103] op_sel_hi:[1,0]
	v_max_f32_e32 v92, 0, v92
	v_max_f32_e32 v88, 0, v88
	v_max_f32_e32 v93, 0, v93
	v_max_f32_e32 v89, 0, v89
	v_max_f32_e32 v94, 0, v94
	v_max_f32_e32 v90, 0, v90
	v_max_f32_e32 v95, 0, v95
	v_max_f32_e32 v91, 0, v91
	v_max_f32_e32 v80, 0, v80
	v_max_f32_e32 v81, 0, v81
	v_max_f32_e32 v82, 0, v82
	v_max_f32_e32 v83, 0, v83
	v_max_f32_e32 v84, 0, v84
	v_max_f32_e32 v85, 0, v85
	v_max_f32_e32 v86, 0, v86
	v_max_f32_e32 v87, 0, v87
	v_mul_f32_e32 v92, v92, v92
	v_mul_f32_e32 v88, v88, v88
	v_mul_f32_e32 v93, v93, v93
	v_mul_f32_e32 v89, v89, v89
	v_mul_f32_e32 v94, v94, v94
	v_mul_f32_e32 v90, v90, v90
	v_mul_f32_e32 v95, v95, v95
	v_mul_f32_e32 v91, v91, v91
	v_mul_f32_e32 v102, v80, v80
	v_mul_f32_e32 v103, v81, v81
	v_mul_f32_e32 v104, v82, v82
	v_mul_f32_e32 v105, v83, v83
	v_cvt_pk_bf16_f32 v80, v92, v93
	v_cvt_pk_bf16_f32 v81, v94, v95
	v_cvt_pk_bf16_f32 v82, v88, v89
	v_cvt_pk_bf16_f32 v83, v90, v91
	v_mul_f32_e32 v84, v84, v84
	v_mul_f32_e32 v85, v85, v85
	v_mul_f32_e32 v86, v86, v86
	v_mul_f32_e32 v87, v87, v87
	global_store_dwordx4 v[98:99], v[80:83], off
	s_nop 1
	v_cvt_pk_bf16_f32 v80, v84, v85
	v_cvt_pk_bf16_f32 v81, v86, v87
	v_cvt_pk_bf16_f32 v82, v102, v103
	v_cvt_pk_bf16_f32 v83, v104, v105
	global_store_dwordx4 v[98:99], v[80:83], off offset:256
	s_nop 0
	s_nop 0
	v_fmamk_f32 v80, v230, 0x3a000000, v158
	v_mul_f32_e32 v81, 0x4f800000, v80
	v_cmp_gt_f32_e32 vcc, s77, v80
	s_nop 1
	v_cndmask_b32_e32 v82, v80, v81, vcc
	v_sqrt_f32_e32 v83, v82
	v_lshlrev_b64 v[80:81], 14, v[96:97]
	v_lshl_add_u64 v[80:81], s[10:11], 0, v[80:81]
	v_lshl_add_u64 v[80:81], v[80:81], 0, v[148:149]
	v_add_u32_e32 v84, -1, v83
	v_add_u32_e32 v85, 1, v83
	v_fma_f32 v86, -v84, v83, v82
	v_fma_f32 v87, -v85, v83, v82
	v_cmp_ge_f32_e64 s[6:7], 0, v86
	s_nop 1
	v_cndmask_b32_e64 v83, v83, v84, s[6:7]
	v_cmp_lt_f32_e64 s[6:7], 0, v87
	s_nop 1
	v_cndmask_b32_e64 v83, v83, v85, s[6:7]
	v_mul_f32_e32 v84, 0x37800000, v83
	v_cndmask_b32_e32 v83, v83, v84, vcc
	v_cmp_class_f32_e32 vcc, v82, v159
	s_nop 1
	v_cndmask_b32_e32 v82, v83, v82, vcc
	v_div_scale_f32 v83, s[0:1], v82, v82, 1.0
	v_rcp_f32_e32 v84, v83
	v_div_scale_f32 v85, vcc, 1.0, v82, 1.0
	v_fma_f32 v86, -v83, v84, 1.0
	v_fmac_f32_e32 v84, v86, v84
	v_mul_f32_e32 v86, v85, v84
	v_fma_f32 v87, -v83, v86, v85
	v_fmac_f32_e32 v86, v87, v84
	v_fma_f32 v83, -v83, v86, v85
	v_div_fmas_f32 v83, v83, v84, v86
	v_div_fixup_f32 v82, v83, v82, 1.0
	v_pk_mul_f32 v[78:79], v[78:79], v[82:83] op_sel_hi:[1,0]
	v_pk_mul_f32 v[76:77], v[76:77], v[82:83] op_sel_hi:[1,0]
	v_pk_mul_f32 v[74:75], v[74:75], v[82:83] op_sel_hi:[1,0]
; __device__ __forceinline__ unsigned cvt_pk_bf16(float lo, float hi) { unsigned r; asm volatile("v_cvt_pk_bf16_f32 %0, %1, %2" : "=v"(r) : "v"(lo), "v"(hi)); return r; }
;     __device__ __forceinline__ void operator()(const f32x4 (&acc)[2][2][4][2], const Unit& u, int wr, int wc, int fr, int fq) const {
;         const int row0 = u.pm * BM + wr * 64 + fr, col0 = u.pn * BM + wc * 32 + 8 * fq;
; #pragma unroll
;         for (int ai = 0; ai < 2; ++ai)
; #pragma unroll
;             for (int m = 0; m < 4; ++m) {
;                 const int row = row0 + ai * HALF + m * 16; const float rs = 1.0f / sqrtf(__hip_atomic_load(ss2 + row, __ATOMIC_RELAXED, __HIP_MEMORY_SCOPE_AGENT) * (1.0f / 2048.0f) + EPSN);
;                 bf16_t* rowp = H + (size_t)row * DFF + col0;
; #pragma unroll
;                 for (int bj = 0; bj < 2; ++bj) {
;                     f32x4 v0 = acc[ai][bj][m][0] * rs, v1 = acc[ai][bj][m][1] * rs;
; #pragma unroll
;                     for (int j = 0; j < 4; ++j) { v0[j] = fmaxf(v0[j], 0.f); v0[j] *= v0[j]; v1[j] = fmaxf(v1[j], 0.f); v1[j] *= v1[j]; }
;                     u32x4 w; w.x = cvt_pk_bf16(v0[0], v0[1]); w.y = cvt_pk_bf16(v0[2], v0[3]); w.z = cvt_pk_bf16(v1[0], v1[1]); w.w = cvt_pk_bf16(v1[2], v1[3]);
;                     *(u32x4*)(rowp + bj * HALF) = w;
	v_pk_mul_f32 v[72:73], v[72:73], v[82:83] op_sel_hi:[1,0]
	v_pk_mul_f32 v[66:67], v[66:67], v[82:83] op_sel_hi:[1,0]
	v_pk_mul_f32 v[64:65], v[64:65], v[82:83] op_sel_hi:[1,0]
	v_pk_mul_f32 v[70:71], v[70:71], v[82:83] op_sel_hi:[1,0]
	v_pk_mul_f32 v[68:69], v[68:69], v[82:83] op_sel_hi:[1,0]
	v_max_f32_e32 v76, 0, v76
	v_max_f32_e32 v72, 0, v72
	v_max_f32_e32 v77, 0, v77
	v_max_f32_e32 v73, 0, v73
	v_max_f32_e32 v78, 0, v78
	v_max_f32_e32 v74, 0, v74
	v_max_f32_e32 v79, 0, v79
	v_max_f32_e32 v75, 0, v75
	v_max_f32_e32 v64, 0, v64
	v_max_f32_e32 v65, 0, v65
	v_max_f32_e32 v66, 0, v66
	v_max_f32_e32 v67, 0, v67
	v_max_f32_e32 v68, 0, v68
	v_max_f32_e32 v69, 0, v69
	v_max_f32_e32 v70, 0, v70
	v_max_f32_e32 v71, 0, v71
	v_mul_f32_e32 v76, v76, v76
	v_mul_f32_e32 v72, v72, v72
	v_mul_f32_e32 v77, v77, v77
	v_mul_f32_e32 v73, v73, v73
	v_mul_f32_e32 v78, v78, v78
	v_mul_f32_e32 v74, v74, v74
	v_mul_f32_e32 v79, v79, v79
	v_mul_f32_e32 v75, v75, v75
	v_mul_f32_e32 v82, v64, v64
	v_mul_f32_e32 v83, v65, v65
	v_mul_f32_e32 v84, v66, v66
	v_mul_f32_e32 v85, v67, v67
	v_cvt_pk_bf16_f32 v64, v76, v77
	v_cvt_pk_bf16_f32 v65, v78, v79
	v_cvt_pk_bf16_f32 v66, v72, v73
	v_cvt_pk_bf16_f32 v67, v74, v75
	v_mul_f32_e32 v68, v68, v68
	v_mul_f32_e32 v69, v69, v69
	v_mul_f32_e32 v70, v70, v70
	v_mul_f32_e32 v71, v71, v71
	global_store_dwordx4 v[80:81], v[64:67], off
	s_nop 1
	v_cvt_pk_bf16_f32 v64, v68, v69
	v_cvt_pk_bf16_f32 v65, v70, v71
	v_cvt_pk_bf16_f32 v66, v82, v83
	v_cvt_pk_bf16_f32 v67, v84, v85
	global_store_dwordx4 v[80:81], v[64:67], off offset:256
	s_nop 0
	s_nop 0
	v_fmamk_f32 v64, v231, 0x3a000000, v158
	v_mul_f32_e32 v65, 0x4f800000, v64
	v_cmp_gt_f32_e32 vcc, s77, v64
	s_nop 1
	v_cndmask_b32_e32 v66, v64, v65, vcc
	v_sqrt_f32_e32 v67, v66
	v_lshl_add_u64 v[64:65], v[146:147], 0, s[40:41]
	v_add_u32_e32 v68, -1, v67
	v_add_u32_e32 v69, 1, v67
	v_fma_f32 v70, -v68, v67, v66
	v_fma_f32 v71, -v69, v67, v66
	v_cmp_ge_f32_e64 s[6:7], 0, v70
	s_nop 1
	v_cndmask_b32_e64 v67, v67, v68, s[6:7]
	v_cmp_lt_f32_e64 s[6:7], 0, v71
	s_nop 1
	v_cndmask_b32_e64 v67, v67, v69, s[6:7]
	v_mul_f32_e32 v68, 0x37800000, v67
	v_cndmask_b32_e32 v67, v67, v68, vcc
	v_cmp_class_f32_e32 vcc, v66, v159
	s_nop 1
	v_cndmask_b32_e32 v68, v67, v66, vcc
	v_div_scale_f32 v69, s[0:1], v68, v68, 1.0
	v_rcp_f32_e32 v70, v69
	v_add_co_u32_e32 v66, vcc, s78, v146
	v_fma_f32 v72, -v69, v70, 1.0
	s_nop 0
	v_addc_co_u32_e32 v67, vcc, 0, v147, vcc
	v_div_scale_f32 v71, vcc, 1.0, v68, 1.0
	v_fmac_f32_e32 v70, v72, v70
	v_mul_f32_e32 v72, v71, v70
	v_fma_f32 v73, -v69, v72, v71
	v_fmac_f32_e32 v72, v73, v70
	v_fma_f32 v69, -v69, v72, v71
	v_div_fmas_f32 v69, v69, v70, v72
	v_div_fixup_f32 v68, v69, v68, 1.0
	v_pk_mul_f32 v[62:63], v[62:63], v[68:69] op_sel_hi:[1,0]
	v_pk_mul_f32 v[60:61], v[60:61], v[68:69] op_sel_hi:[1,0]
	v_pk_mul_f32 v[58:59], v[58:59], v[68:69] op_sel_hi:[1,0]
	v_pk_mul_f32 v[56:57], v[56:57], v[68:69] op_sel_hi:[1,0]
	v_pk_mul_f32 v[50:51], v[50:51], v[68:69] op_sel_hi:[1,0]
	v_pk_mul_f32 v[48:49], v[48:49], v[68:69] op_sel_hi:[1,0]
	v_pk_mul_f32 v[54:55], v[54:55], v[68:69] op_sel_hi:[1,0]
	v_pk_mul_f32 v[52:53], v[52:53], v[68:69] op_sel_hi:[1,0]
	v_max_f32_e32 v60, 0, v60
	v_max_f32_e32 v56, 0, v56
	v_max_f32_e32 v61, 0, v61
	v_max_f32_e32 v57, 0, v57
	v_max_f32_e32 v62, 0, v62
	v_max_f32_e32 v58, 0, v58
	v_max_f32_e32 v63, 0, v63
	v_max_f32_e32 v59, 0, v59
	v_max_f32_e32 v48, 0, v48
	v_max_f32_e32 v49, 0, v49
	v_max_f32_e32 v50, 0, v50
	v_max_f32_e32 v51, 0, v51
	v_max_f32_e32 v52, 0, v52
	v_max_f32_e32 v53, 0, v53
	v_max_f32_e32 v54, 0, v54
	v_max_f32_e32 v55, 0, v55
	v_mul_f32_e32 v60, v60, v60
	v_mul_f32_e32 v56, v56, v56
	v_mul_f32_e32 v61, v61, v61
	v_mul_f32_e32 v57, v57, v57
	v_mul_f32_e32 v62, v62, v62
	v_mul_f32_e32 v58, v58, v58
	v_mul_f32_e32 v63, v63, v63
	v_mul_f32_e32 v59, v59, v59
	v_mul_f32_e32 v68, v48, v48
	v_mul_f32_e32 v69, v49, v49
	v_mul_f32_e32 v70, v50, v50
	v_mul_f32_e32 v71, v51, v51
	v_cvt_pk_bf16_f32 v48, v60, v61
	v_cvt_pk_bf16_f32 v49, v62, v63
	v_cvt_pk_bf16_f32 v50, v56, v57
	v_cvt_pk_bf16_f32 v51, v58, v59
	v_mul_f32_e32 v52, v52, v52
	v_mul_f32_e32 v53, v53, v53
	v_mul_f32_e32 v54, v54, v54
	v_mul_f32_e32 v55, v55, v55
	global_store_dwordx4 v[66:67], v[48:51], off
	s_nop 1
	v_cvt_pk_bf16_f32 v48, v52, v53
	v_cvt_pk_bf16_f32 v49, v54, v55
	v_cvt_pk_bf16_f32 v50, v68, v69
	v_cvt_pk_bf16_f32 v51, v70, v71
	global_store_dwordx4 v[64:65], v[48:51], off offset:256
	s_nop 0
	s_nop 0
	v_fmamk_f32 v48, v232, 0x3a000000, v158
	v_mul_f32_e32 v49, 0x4f800000, v48
	v_cmp_gt_f32_e32 vcc, s77, v48
	s_nop 1
	v_cndmask_b32_e32 v50, v48, v49, vcc
	v_sqrt_f32_e32 v51, v50
	v_lshl_add_u64 v[48:49], v[146:147], 0, s[42:43]
	v_add_u32_e32 v52, -1, v51
	v_add_u32_e32 v53, 1, v51
	v_fma_f32 v54, -v52, v51, v50
	v_fma_f32 v55, -v53, v51, v50
	v_cmp_ge_f32_e64 s[6:7], 0, v54
	s_nop 1
	v_cndmask_b32_e64 v51, v51, v52, s[6:7]
	v_cmp_lt_f32_e64 s[6:7], 0, v55
	s_nop 1
	v_cndmask_b32_e64 v51, v51, v53, s[6:7]
	v_mul_f32_e32 v52, 0x37800000, v51
	v_cndmask_b32_e32 v51, v51, v52, vcc
	v_cmp_class_f32_e32 vcc, v50, v159
	s_nop 1
	v_cndmask_b32_e32 v52, v51, v50, vcc
	v_div_scale_f32 v53, s[0:1], v52, v52, 1.0
	v_rcp_f32_e32 v54, v53
	v_add_co_u32_e32 v50, vcc, s79, v146
	v_fma_f32 v56, -v53, v54, 1.0
	s_nop 0
	v_addc_co_u32_e32 v51, vcc, 0, v147, vcc
	v_div_scale_f32 v55, vcc, 1.0, v52, 1.0
	v_fmac_f32_e32 v54, v56, v54
	v_mul_f32_e32 v56, v55, v54
	v_fma_f32 v57, -v53, v56, v55
	v_fmac_f32_e32 v56, v57, v54
	v_fma_f32 v53, -v53, v56, v55
	v_div_fmas_f32 v53, v53, v54, v56
	v_div_fixup_f32 v52, v53, v52, 1.0
	v_pk_mul_f32 v[46:47], v[46:47], v[52:53] op_sel_hi:[1,0]
; __device__ __forceinline__ unsigned cvt_pk_bf16(float lo, float hi) { unsigned r; asm volatile("v_cvt_pk_bf16_f32 %0, %1, %2" : "=v"(r) : "v"(lo), "v"(hi)); return r; }
;     __device__ __forceinline__ void operator()(const f32x4 (&acc)[2][2][4][2], const Unit& u, int wr, int wc, int fr, int fq) const {
;         const int row0 = u.pm * BM + wr * 64 + fr, col0 = u.pn * BM + wc * 32 + 8 * fq;
; #pragma unroll
;         for (int ai = 0; ai < 2; ++ai)
; #pragma unroll
;             for (int m = 0; m < 4; ++m) {
;                 const int row = row0 + ai * HALF + m * 16; const float rs = 1.0f / sqrtf(__hip_atomic_load(ss2 + row, __ATOMIC_RELAXED, __HIP_MEMORY_SCOPE_AGENT) * (1.0f / 2048.0f) + EPSN);
;                 bf16_t* rowp = H + (size_t)row * DFF + col0;
; #pragma unroll
;                 for (int bj = 0; bj < 2; ++bj) {
;                     f32x4 v0 = acc[ai][bj][m][0] * rs, v1 = acc[ai][bj][m][1] * rs;
; #pragma unroll
;                     for (int j = 0; j < 4; ++j) { v0[j] = fmaxf(v0[j], 0.f); v0[j] *= v0[j]; v1[j] = fmaxf(v1[j], 0.f); v1[j] *= v1[j]; }
;                     u32x4 w; w.x = cvt_pk_bf16(v0[0], v0[1]); w.y = cvt_pk_bf16(v0[2], v0[3]); w.z = cvt_pk_bf16(v1[0], v1[1]); w.w = cvt_pk_bf16(v1[2], v1[3]);
;                     *(u32x4*)(rowp + bj * HALF) = w;
	v_pk_mul_f32 v[44:45], v[44:45], v[52:53] op_sel_hi:[1,0]
	v_pk_mul_f32 v[42:43], v[42:43], v[52:53] op_sel_hi:[1,0]
	v_pk_mul_f32 v[40:41], v[40:41], v[52:53] op_sel_hi:[1,0]
	v_pk_mul_f32 v[34:35], v[34:35], v[52:53] op_sel_hi:[1,0]
	v_pk_mul_f32 v[32:33], v[32:33], v[52:53] op_sel_hi:[1,0]
	v_pk_mul_f32 v[38:39], v[38:39], v[52:53] op_sel_hi:[1,0]
	v_pk_mul_f32 v[36:37], v[36:37], v[52:53] op_sel_hi:[1,0]
	v_max_f32_e32 v44, 0, v44
	v_max_f32_e32 v40, 0, v40
	v_max_f32_e32 v45, 0, v45
	v_max_f32_e32 v41, 0, v41
	v_max_f32_e32 v46, 0, v46
	v_max_f32_e32 v42, 0, v42
	v_max_f32_e32 v47, 0, v47
	v_max_f32_e32 v43, 0, v43
	v_max_f32_e32 v32, 0, v32
	v_max_f32_e32 v33, 0, v33
	v_max_f32_e32 v34, 0, v34
	v_max_f32_e32 v35, 0, v35
	v_max_f32_e32 v36, 0, v36
	v_max_f32_e32 v37, 0, v37
	v_max_f32_e32 v38, 0, v38
	v_max_f32_e32 v39, 0, v39
	v_mul_f32_e32 v44, v44, v44
	v_mul_f32_e32 v40, v40, v40
	v_mul_f32_e32 v45, v45, v45
	v_mul_f32_e32 v41, v41, v41
	v_mul_f32_e32 v46, v46, v46
	v_mul_f32_e32 v42, v42, v42
	v_mul_f32_e32 v47, v47, v47
	v_mul_f32_e32 v43, v43, v43
	v_mul_f32_e32 v52, v32, v32
	v_mul_f32_e32 v53, v33, v33
	v_mul_f32_e32 v54, v34, v34
	v_mul_f32_e32 v55, v35, v35
	v_cvt_pk_bf16_f32 v32, v44, v45
	v_cvt_pk_bf16_f32 v33, v46, v47
	v_cvt_pk_bf16_f32 v34, v40, v41
	v_cvt_pk_bf16_f32 v35, v42, v43
	v_mul_f32_e32 v36, v36, v36
	v_mul_f32_e32 v37, v37, v37
	v_mul_f32_e32 v38, v38, v38
	v_mul_f32_e32 v39, v39, v39
	global_store_dwordx4 v[50:51], v[32:35], off
	s_nop 1
	v_cvt_pk_bf16_f32 v32, v36, v37
	v_cvt_pk_bf16_f32 v33, v38, v39
	v_cvt_pk_bf16_f32 v34, v52, v53
	v_cvt_pk_bf16_f32 v35, v54, v55
	global_store_dwordx4 v[48:49], v[32:35], off offset:256
	s_nop 0
	s_nop 0
	v_fmamk_f32 v32, v233, 0x3a000000, v158
	v_mul_f32_e32 v33, 0x4f800000, v32
	v_cmp_gt_f32_e32 vcc, s77, v32
	s_nop 1
	v_cndmask_b32_e32 v34, v32, v33, vcc
	v_sqrt_f32_e32 v35, v34
	v_lshl_add_u64 v[32:33], v[146:147], 0, s[44:45]
	v_add_u32_e32 v36, -1, v35
	v_add_u32_e32 v37, 1, v35
	v_fma_f32 v38, -v36, v35, v34
	v_fma_f32 v39, -v37, v35, v34
	v_cmp_ge_f32_e64 s[6:7], 0, v38
	s_nop 1
	v_cndmask_b32_e64 v35, v35, v36, s[6:7]
	v_cmp_lt_f32_e64 s[6:7], 0, v39
	s_nop 1
	v_cndmask_b32_e64 v35, v35, v37, s[6:7]
	v_mul_f32_e32 v36, 0x37800000, v35
	v_cndmask_b32_e32 v35, v35, v36, vcc
	v_cmp_class_f32_e32 vcc, v34, v159
	s_nop 1
	v_cndmask_b32_e32 v36, v35, v34, vcc
	v_div_scale_f32 v37, s[0:1], v36, v36, 1.0
	v_rcp_f32_e32 v38, v37
	v_add_co_u32_e32 v34, vcc, s80, v146
	v_fma_f32 v40, -v37, v38, 1.0
	s_nop 0
	v_addc_co_u32_e32 v35, vcc, 0, v147, vcc
	v_div_scale_f32 v39, vcc, 1.0, v36, 1.0
	v_fmac_f32_e32 v38, v40, v38
	v_mul_f32_e32 v40, v39, v38
	v_fma_f32 v41, -v37, v40, v39
	v_fmac_f32_e32 v40, v41, v38
	v_fma_f32 v37, -v37, v40, v39
	v_div_fmas_f32 v37, v37, v38, v40
	v_div_fixup_f32 v36, v37, v36, 1.0
	v_pk_mul_f32 v[30:31], v[30:31], v[36:37] op_sel_hi:[1,0]
	v_pk_mul_f32 v[28:29], v[28:29], v[36:37] op_sel_hi:[1,0]
	v_pk_mul_f32 v[26:27], v[26:27], v[36:37] op_sel_hi:[1,0]
	v_pk_mul_f32 v[24:25], v[24:25], v[36:37] op_sel_hi:[1,0]
	v_pk_mul_f32 v[18:19], v[18:19], v[36:37] op_sel_hi:[1,0]
	v_pk_mul_f32 v[16:17], v[16:17], v[36:37] op_sel_hi:[1,0]
	v_pk_mul_f32 v[22:23], v[22:23], v[36:37] op_sel_hi:[1,0]
	v_pk_mul_f32 v[20:21], v[20:21], v[36:37] op_sel_hi:[1,0]
	v_max_f32_e32 v28, 0, v28
	v_max_f32_e32 v24, 0, v24
	v_max_f32_e32 v29, 0, v29
	v_max_f32_e32 v25, 0, v25
	v_max_f32_e32 v30, 0, v30
	v_max_f32_e32 v26, 0, v26
	v_max_f32_e32 v31, 0, v31
	v_max_f32_e32 v27, 0, v27
	v_max_f32_e32 v16, 0, v16
	v_max_f32_e32 v17, 0, v17
	v_max_f32_e32 v18, 0, v18
	v_max_f32_e32 v19, 0, v19
	v_max_f32_e32 v20, 0, v20
	v_max_f32_e32 v21, 0, v21
	v_max_f32_e32 v22, 0, v22
	v_max_f32_e32 v23, 0, v23
	v_mul_f32_e32 v28, v28, v28
; __device__ __forceinline__ unsigned cvt_pk_bf16(float lo, float hi) { unsigned r; asm volatile("v_cvt_pk_bf16_f32 %0, %1, %2" : "=v"(r) : "v"(lo), "v"(hi)); return r; }
; #define PG8_BAR __builtin_amdgcn_s_barrier()
;     __device__ __forceinline__ void operator()(const f32x4 (&acc)[2][2][4][2], const Unit& u, int wr, int wc, int fr, int fq) const {
;         const int row0 = u.pm * BM + wr * 64 + fr, col0 = u.pn * BM + wc * 32 + 8 * fq;
; #pragma unroll
;         for (int ai = 0; ai < 2; ++ai)
; #pragma unroll
;             for (int m = 0; m < 4; ++m) {
;                 const int row = row0 + ai * HALF + m * 16; const float rs = 1.0f / sqrtf(__hip_atomic_load(ss2 + row, __ATOMIC_RELAXED, __HIP_MEMORY_SCOPE_AGENT) * (1.0f / 2048.0f) + EPSN);
;                 bf16_t* rowp = H + (size_t)row * DFF + col0;
; #pragma unroll
;                 for (int bj = 0; bj < 2; ++bj) {
;                     f32x4 v0 = acc[ai][bj][m][0] * rs, v1 = acc[ai][bj][m][1] * rs;
; #pragma unroll
;                     for (int j = 0; j < 4; ++j) { v0[j] = fmaxf(v0[j], 0.f); v0[j] *= v0[j]; v1[j] = fmaxf(v1[j], 0.f); v1[j] *= v1[j]; }
;                     u32x4 w; w.x = cvt_pk_bf16(v0[0], v0[1]); w.y = cvt_pk_bf16(v0[2], v0[3]); w.z = cvt_pk_bf16(v1[0], v1[1]); w.w = cvt_pk_bf16(v1[2], v1[3]);
;                     *(u32x4*)(rowp + bj * HALF) = w;
; template <class Epi, class Sched, bool ALIGN_EPI = false, bool SP2 = false>
; __device__ __forceinline__ void gemm_phase(PG8_LAS unsigned char* lds, const Gemm g, const Sched& S, const Epi& E) {
;     ...
;         else if constexpr (!Epi::AFTER_DRAIN) { E(acc, cur, wr, wc, fr, fq); S.done(cur); }
;         if (!has_next) break;
;         if (!keep) {
; #pragma unroll
;         for (int a = 0; a < 2; ++a)
; #pragma unroll
;             for (int b = 0; b < 2; ++b)
; #pragma unroll
;                 for (int m = 0; m < 4; ++m)
; #pragma unroll
;                     for (int n = 0; n < 2; ++n) acc[a][b][m][n] = (f32x4){0.f, 0.f, 0.f, 0.f};
;         }
;         cur = nxt; cA = nA; cB = nB; ++ui;
;         if constexpr (ALIGN_EPI) { if (wr == 1) PG8_BAR; }
	v_mul_f32_e32 v24, v24, v24
	v_mul_f32_e32 v29, v29, v29
	v_mul_f32_e32 v25, v25, v25
	v_mul_f32_e32 v30, v30, v30
	v_mul_f32_e32 v26, v26, v26
	v_mul_f32_e32 v31, v31, v31
	v_mul_f32_e32 v27, v27, v27
	v_mul_f32_e32 v36, v16, v16
	v_mul_f32_e32 v37, v17, v17
	v_mul_f32_e32 v38, v18, v18
	v_mul_f32_e32 v39, v19, v19
	v_cvt_pk_bf16_f32 v16, v28, v29
	v_cvt_pk_bf16_f32 v17, v30, v31
	v_cvt_pk_bf16_f32 v18, v24, v25
	v_cvt_pk_bf16_f32 v19, v26, v27
	v_mul_f32_e32 v20, v20, v20
	v_mul_f32_e32 v21, v21, v21
	v_mul_f32_e32 v22, v22, v22
	v_mul_f32_e32 v23, v23, v23
	global_store_dwordx4 v[34:35], v[16:19], off
	s_nop 1
	v_cvt_pk_bf16_f32 v16, v20, v21
	v_cvt_pk_bf16_f32 v17, v22, v23
	v_cvt_pk_bf16_f32 v18, v36, v37
	v_cvt_pk_bf16_f32 v19, v38, v39
	global_store_dwordx4 v[32:33], v[16:19], off offset:256
	s_nop 0
	s_nop 0
	v_fmamk_f32 v16, v234, 0x3a000000, v158
	v_mul_f32_e32 v17, 0x4f800000, v16
	v_cmp_gt_f32_e32 vcc, s77, v16
	s_nop 1
	v_cndmask_b32_e32 v18, v16, v17, vcc
	v_sqrt_f32_e32 v19, v18
	v_lshl_add_u64 v[16:17], v[146:147], 0, s[46:47]
	v_add_u32_e32 v20, -1, v19
	v_add_u32_e32 v21, 1, v19
	v_fma_f32 v22, -v20, v19, v18
	v_fma_f32 v23, -v21, v19, v18
	v_cmp_ge_f32_e64 s[6:7], 0, v22
	s_nop 1
	v_cndmask_b32_e64 v19, v19, v20, s[6:7]
	v_cmp_lt_f32_e64 s[6:7], 0, v23
	s_nop 1
	v_cndmask_b32_e64 v19, v19, v21, s[6:7]
	v_mul_f32_e32 v20, 0x37800000, v19
	v_cndmask_b32_e32 v19, v19, v20, vcc
	v_cmp_class_f32_e32 vcc, v18, v159
	s_nop 1
	v_cndmask_b32_e32 v20, v19, v18, vcc
	v_div_scale_f32 v21, s[0:1], v20, v20, 1.0
	v_rcp_f32_e32 v22, v21
	v_add_co_u32_e32 v18, vcc, s81, v146
	v_fma_f32 v24, -v21, v22, 1.0
	s_nop 0
	v_addc_co_u32_e32 v19, vcc, 0, v147, vcc
	v_div_scale_f32 v23, vcc, 1.0, v20, 1.0
	v_fmac_f32_e32 v22, v24, v22
	v_mul_f32_e32 v24, v23, v22
	v_fma_f32 v25, -v21, v24, v23
	v_fmac_f32_e32 v24, v25, v22
	v_fma_f32 v21, -v21, v24, v23
	v_div_fmas_f32 v21, v21, v22, v24
	v_div_fixup_f32 v20, v21, v20, 1.0
	v_pk_mul_f32 v[14:15], v[14:15], v[20:21] op_sel_hi:[1,0]
	v_pk_mul_f32 v[12:13], v[12:13], v[20:21] op_sel_hi:[1,0]
	v_pk_mul_f32 v[10:11], v[10:11], v[20:21] op_sel_hi:[1,0]
	v_pk_mul_f32 v[8:9], v[8:9], v[20:21] op_sel_hi:[1,0]
	v_pk_mul_f32 v[2:3], v[2:3], v[20:21] op_sel_hi:[1,0]
	v_pk_mul_f32 v[0:1], v[0:1], v[20:21] op_sel_hi:[1,0]
	v_pk_mul_f32 v[6:7], v[6:7], v[20:21] op_sel_hi:[1,0]
	v_pk_mul_f32 v[4:5], v[4:5], v[20:21] op_sel_hi:[1,0]
	v_max_f32_e32 v12, 0, v12
	v_max_f32_e32 v8, 0, v8
	v_max_f32_e32 v13, 0, v13
	v_max_f32_e32 v9, 0, v9
	v_max_f32_e32 v14, 0, v14
	v_max_f32_e32 v10, 0, v10
	v_max_f32_e32 v15, 0, v15
	v_max_f32_e32 v11, 0, v11
	v_max_f32_e32 v0, 0, v0
	v_max_f32_e32 v1, 0, v1
	v_max_f32_e32 v2, 0, v2
	v_max_f32_e32 v3, 0, v3
	s_andn2_b64 vcc, exec, s[4:5]
	v_max_f32_e32 v4, 0, v4
	v_max_f32_e32 v5, 0, v5
	v_max_f32_e32 v6, 0, v6
	v_max_f32_e32 v7, 0, v7
	v_mul_f32_e32 v12, v12, v12
	v_mul_f32_e32 v8, v8, v8
	v_mul_f32_e32 v13, v13, v13
	v_mul_f32_e32 v9, v9, v9
	v_mul_f32_e32 v14, v14, v14
	v_mul_f32_e32 v10, v10, v10
	v_mul_f32_e32 v15, v15, v15
	v_mul_f32_e32 v11, v11, v11
	v_mul_f32_e32 v20, v0, v0
	v_mul_f32_e32 v21, v1, v1
	v_mul_f32_e32 v22, v2, v2
	v_mul_f32_e32 v23, v3, v3
	v_cvt_pk_bf16_f32 v0, v12, v13
	v_cvt_pk_bf16_f32 v1, v14, v15
	v_cvt_pk_bf16_f32 v2, v8, v9
	v_cvt_pk_bf16_f32 v3, v10, v11
	s_mov_b64 s[4:5], -1
	v_mul_f32_e32 v4, v4, v4
	v_mul_f32_e32 v5, v5, v5
	v_mul_f32_e32 v6, v6, v6
	v_mul_f32_e32 v7, v7, v7
	global_store_dwordx4 v[18:19], v[0:3], off
	s_nop 1
	v_cvt_pk_bf16_f32 v0, v4, v5
	v_cvt_pk_bf16_f32 v1, v6, v7
	v_cvt_pk_bf16_f32 v2, v20, v21
	v_cvt_pk_bf16_f32 v3, v22, v23
	global_store_dwordx4 v[16:17], v[0:3], off offset:256
	s_cbranch_vccnz .LBB0_1053
	s_andn2_b64 vcc, exec, s[22:23]
	s_cbranch_vccnz .LBB0_1052
	s_barrier
	s_branch .LBB0_1052
